# EpiUq: row-scale sums preloaded in the last K iteration, all cos/sin loads at epilogue start
# speedup vs baseline: 1.0052x; 1.0052x over previous
.LBB0_268:
	s_add_u32 s24, s2, 0x100
	s_addc_u32 s25, s3, 0
	s_add_i32 s0, 0, 0x10000
	s_cmp_eq_u32 s44, 2
	s_cselect_b32 s41, s19, s25
	s_cselect_b32 s40, s18, s24
	v_add_u32_e32 v0, s0, v178
	s_cselect_b32 s39, s79, s43
	s_cselect_b32 s38, s78, s42
	s_add_i32 s45, 0, 0x14000
	ds_read_b128 v[50:53], v0
	ds_read_b128 v[54:57], v0 offset:1024
	ds_read_b128 v[150:153], v0 offset:2048
	ds_read_b128 v[154:157], v0 offset:3072
	v_add_u32_e32 v0, s45, v178
	ds_read_b128 v[158:161], v0
	ds_read_b128 v[162:165], v0 offset:1024
	ds_read_b128 v[166:169], v0 offset:2048
	ds_read_b128 v[170:173], v0 offset:3072
	s_cmp_eq_u32 s44, 2
	s_cbranch_scc0 .Luq_pa_skip
	s_lshl_b32 s100, s29, 8
	s_add_i32 s100, s100, s82
	v_and_or_b32 v252, v193, 15, s100
	v_bfe_u32 v253, v193, 4, 2
	v_lshlrev_b32_e32 v253, 4, v253
	v_mul_u32_u24_e32 v252, 0x60, v252
	v_add_u32_e32 v252, v252, v253
	global_load_dwordx4 v[194:197], v252, s[16:17]
	global_load_dwordx4 v[198:201], v252, s[16:17] offset:1536
	global_load_dwordx4 v[202:205], v252, s[16:17] offset:3072
	v_add_u32_e32 v253, 0x1200, v252
	global_load_dwordx4 v[206:209], v253, s[16:17]
.Luq_pa_skip:
	v_lshl_add_u64 v[218:219], s[2:3], 0, v[148:149]
	s_add_i32 m0, s76, 0xc000
	ds_read_b128 v[174:177], v179
	ds_read_b128 v[180:183], v179 offset:1024
	ds_read_b128 v[184:187], v179 offset:2048
	ds_read_b128 v[188:191], v179 offset:3072
	ds_read_b128 v[214:217], v179 offset:4096
	ds_read_b128 v[228:231], v179 offset:5120
	ds_read_b128 v[232:235], v179 offset:6144
	ds_read_b128 v[236:239], v179 offset:7168
	global_load_lds_dwordx4 v[218:219], off
	v_lshl_add_u64 v[218:219], s[2:3], 0, v[146:147]
	s_add_i32 m0, s76, 0xe000
	s_nop 0
	global_load_lds_dwordx4 v[218:219], off
	s_waitcnt vmcnt(8)
	s_waitcnt lgkmcnt(0)
	s_barrier
	s_setprio 1
	s_waitcnt lgkmcnt(0)
	v_mfma_f32_16x16x32_bf16 v[134:137], v[50:53], v[174:177], v[134:137]
	v_mfma_f32_16x16x32_bf16 v[130:133], v[150:153], v[174:177], v[130:133]
	v_mfma_f32_16x16x32_bf16 v[118:121], v[50:53], v[184:187], v[118:121]
	v_mfma_f32_16x16x32_bf16 v[114:117], v[150:153], v[184:187], v[114:117]
	v_mfma_f32_16x16x32_bf16 v[102:105], v[50:53], v[214:217], v[102:105]
	v_mfma_f32_16x16x32_bf16 v[98:101], v[150:153], v[214:217], v[98:101]
	v_mfma_f32_16x16x32_bf16 v[86:89], v[50:53], v[232:235], v[86:89]
	v_mfma_f32_16x16x32_bf16 v[82:85], v[150:153], v[232:235], v[82:85]
	v_mfma_f32_16x16x32_bf16 v[134:137], v[54:57], v[180:183], v[134:137]
	v_mfma_f32_16x16x32_bf16 v[130:133], v[154:157], v[180:183], v[130:133]
	v_mfma_f32_16x16x32_bf16 v[118:121], v[54:57], v[188:191], v[118:121]
	v_mfma_f32_16x16x32_bf16 v[114:117], v[154:157], v[188:191], v[114:117]
	v_mfma_f32_16x16x32_bf16 v[102:105], v[54:57], v[228:231], v[102:105]
	v_mfma_f32_16x16x32_bf16 v[98:101], v[154:157], v[228:231], v[98:101]
	v_mfma_f32_16x16x32_bf16 v[86:89], v[54:57], v[236:239], v[86:89]
	v_mfma_f32_16x16x32_bf16 v[82:85], v[154:157], v[236:239], v[82:85]
	s_setprio 0
	s_setprio 1
	v_mfma_f32_16x16x32_bf16 v[126:129], v[158:161], v[174:177], v[126:129]
	v_mfma_f32_16x16x32_bf16 v[122:125], v[166:169], v[174:177], v[122:125]
	v_mfma_f32_16x16x32_bf16 v[110:113], v[158:161], v[184:187], v[110:113]
	v_mfma_f32_16x16x32_bf16 v[106:109], v[166:169], v[184:187], v[106:109]
	v_mfma_f32_16x16x32_bf16 v[94:97], v[158:161], v[214:217], v[94:97]
	v_mfma_f32_16x16x32_bf16 v[90:93], v[166:169], v[214:217], v[90:93]
	v_mfma_f32_16x16x32_bf16 v[78:81], v[158:161], v[232:235], v[78:81]
	v_mfma_f32_16x16x32_bf16 v[74:77], v[166:169], v[232:235], v[74:77]
	v_mfma_f32_16x16x32_bf16 v[126:129], v[162:165], v[180:183], v[126:129]
	v_mfma_f32_16x16x32_bf16 v[122:125], v[170:173], v[180:183], v[122:125]
	v_mfma_f32_16x16x32_bf16 v[110:113], v[162:165], v[188:191], v[110:113]
	v_mfma_f32_16x16x32_bf16 v[106:109], v[170:173], v[188:191], v[106:109]
	v_mfma_f32_16x16x32_bf16 v[94:97], v[162:165], v[228:231], v[94:97]
	v_mfma_f32_16x16x32_bf16 v[90:93], v[170:173], v[228:231], v[90:93]
	v_mfma_f32_16x16x32_bf16 v[78:81], v[162:165], v[236:239], v[78:81]
	v_mfma_f32_16x16x32_bf16 v[74:77], v[170:173], v[236:239], v[74:77]
	s_setprio 0
	s_barrier
	s_add_i32 s0, s0, s75
	v_lshl_add_u64 v[218:219], s[38:39], 0, v[142:143]
	s_mov_b32 m0, s0
	ds_read_b128 v[174:177], v179 offset:16384
	ds_read_b128 v[180:183], v179 offset:17408
	ds_read_b128 v[184:187], v179 offset:18432
	ds_read_b128 v[188:191], v179 offset:19456
	ds_read_b128 v[214:217], v179 offset:20480
	ds_read_b128 v[228:231], v179 offset:21504
	ds_read_b128 v[232:235], v179 offset:22528
	ds_read_b128 v[236:239], v179 offset:23552
	global_load_lds_dwordx4 v[218:219], off
	s_add_i32 m0, s0, 0x2000
	s_add_u32 s2, s38, 0x18000
	v_lshl_add_u64 v[240:241], s[38:39], 0, v[138:139]
	s_addc_u32 s3, s39, 0
	s_add_i32 s0, s45, s75
	global_load_lds_dwordx4 v[240:241], off
	v_lshl_add_u64 v[242:243], s[2:3], 0, v[142:143]
	s_mov_b32 m0, s0
	v_lshl_add_u64 v[244:245], s[40:41], 0, v[140:141]
	global_load_lds_dwordx4 v[242:243], off
	v_lshl_add_u64 v[242:243], s[2:3], 0, v[138:139]
	s_add_i32 m0, s0, 0x2000
	s_nop 0
	global_load_lds_dwordx4 v[242:243], off
	v_lshl_add_u64 v[242:243], s[40:41], 0, v[144:145]
	s_mov_b32 m0, s76
	s_nop 0
	global_load_lds_dwordx4 v[242:243], off
	s_mov_b32 m0, s51
	s_nop 0
	global_load_lds_dwordx4 v[244:245], off
	s_waitcnt vmcnt(8)
	s_waitcnt lgkmcnt(0)
	s_barrier
	s_setprio 1
	s_waitcnt lgkmcnt(0)
	v_mfma_f32_16x16x32_bf16 v[70:73], v[50:53], v[174:177], v[70:73]
	v_mfma_f32_16x16x32_bf16 v[66:69], v[150:153], v[174:177], v[66:69]
	v_mfma_f32_16x16x32_bf16 v[46:49], v[50:53], v[184:187], v[46:49]
	v_mfma_f32_16x16x32_bf16 v[42:45], v[150:153], v[184:187], v[42:45]
	v_mfma_f32_16x16x32_bf16 v[30:33], v[50:53], v[214:217], v[30:33]
	v_mfma_f32_16x16x32_bf16 v[26:29], v[150:153], v[214:217], v[26:29]
	v_mfma_f32_16x16x32_bf16 v[14:17], v[50:53], v[232:235], v[14:17]
	v_mfma_f32_16x16x32_bf16 v[10:13], v[150:153], v[232:235], v[10:13]
	v_mfma_f32_16x16x32_bf16 v[70:73], v[54:57], v[180:183], v[70:73]
	v_mfma_f32_16x16x32_bf16 v[66:69], v[154:157], v[180:183], v[66:69]
	v_mfma_f32_16x16x32_bf16 v[46:49], v[54:57], v[188:191], v[46:49]
	v_mfma_f32_16x16x32_bf16 v[42:45], v[154:157], v[188:191], v[42:45]
	v_mfma_f32_16x16x32_bf16 v[30:33], v[54:57], v[228:231], v[30:33]
	v_mfma_f32_16x16x32_bf16 v[26:29], v[154:157], v[228:231], v[26:29]
	v_mfma_f32_16x16x32_bf16 v[14:17], v[54:57], v[236:239], v[14:17]
	v_mfma_f32_16x16x32_bf16 v[10:13], v[154:157], v[236:239], v[10:13]
	s_setprio 0
	s_setprio 1
	v_mfma_f32_16x16x32_bf16 v[38:41], v[158:161], v[184:187], v[38:41]
	v_mfma_f32_16x16x32_bf16 v[34:37], v[166:169], v[184:187], v[34:37]
	v_mfma_f32_16x16x32_bf16 v[22:25], v[158:161], v[214:217], v[22:25]
	v_mfma_f32_16x16x32_bf16 v[18:21], v[166:169], v[214:217], v[18:21]
	v_mfma_f32_16x16x32_bf16 v[6:9], v[158:161], v[232:235], v[6:9]
	v_mfma_f32_16x16x32_bf16 v[2:5], v[166:169], v[232:235], v[2:5]
	v_mfma_f32_16x16x32_bf16 v[50:53], v[158:161], v[174:177], v[62:65]
	v_mfma_f32_16x16x32_bf16 v[54:57], v[166:169], v[174:177], v[58:61]
	v_mfma_f32_16x16x32_bf16 v[38:41], v[162:165], v[188:191], v[38:41]
	v_mfma_f32_16x16x32_bf16 v[34:37], v[170:173], v[188:191], v[34:37]
	v_mfma_f32_16x16x32_bf16 v[22:25], v[162:165], v[228:231], v[22:25]
	v_mfma_f32_16x16x32_bf16 v[18:21], v[170:173], v[228:231], v[18:21]
	v_mfma_f32_16x16x32_bf16 v[6:9], v[162:165], v[236:239], v[6:9]
	v_mfma_f32_16x16x32_bf16 v[2:5], v[170:173], v[236:239], v[2:5]
	v_mfma_f32_16x16x32_bf16 v[50:53], v[162:165], v[180:183], v[50:53]
	v_mfma_f32_16x16x32_bf16 v[54:57], v[170:173], v[180:183], v[54:57]
	s_setprio 0
	s_barrier
	s_add_i32 s0, 0, 0x18000
	v_add_u32_e32 v0, s0, v178
	s_add_i32 s45, 0, 0x1c000
	ds_read_b128 v[58:61], v0
	ds_read_b128 v[62:65], v0 offset:1024
	ds_read_b128 v[150:153], v0 offset:2048
	ds_read_b128 v[154:157], v0 offset:3072
	v_add_u32_e32 v0, s45, v178
	ds_read_b128 v[158:161], v0
	ds_read_b128 v[162:165], v0 offset:1024
	ds_read_b128 v[166:169], v0 offset:2048
	ds_read_b128 v[170:173], v0 offset:3072
	s_add_u32 s2, s40, 0x30000
	s_addc_u32 s3, s41, 0
	s_mov_b32 m0, s77
	v_lshl_add_u64 v[246:247], s[2:3], 0, v[144:145]
	ds_read_b128 v[174:177], v179 offset:32768
	ds_read_b128 v[180:183], v179 offset:33792
	ds_read_b128 v[184:187], v179 offset:34816
	ds_read_b128 v[188:191], v179 offset:35840
	ds_read_b128 v[214:217], v179 offset:36864
	ds_read_b128 v[228:231], v179 offset:37888
	ds_read_b128 v[232:235], v179 offset:38912
	ds_read_b128 v[236:239], v179 offset:39936
	s_cmp_eq_u32 s44, 2
	s_cbranch_scc0 .Luq_pb_skip
	v_add_f32_e32 v221, v195, v194
	v_add_f32_e32 v253, v196, v197
	v_add_f32_e32 v221, v221, v253
	v_add_f32_e32 v222, v199, v198
	v_add_f32_e32 v253, v200, v201
	v_add_f32_e32 v222, v222, v253
	v_add_f32_e32 v223, v203, v202
	v_add_f32_e32 v253, v204, v205
	v_add_f32_e32 v223, v223, v253
	v_add_f32_e32 v224, v207, v206
	v_add_f32_e32 v253, v208, v209
	v_add_f32_e32 v224, v224, v253
	v_add_u32_e32 v253, 0x3000, v252
	global_load_dwordx4 v[194:197], v253, s[16:17]
	global_load_dwordx4 v[198:201], v253, s[16:17] offset:1536
	global_load_dwordx4 v[202:205], v253, s[16:17] offset:3072
	v_add_u32_e32 v254, 0x4200, v252
	global_load_dwordx4 v[206:209], v254, s[16:17]
.Luq_pb_skip:
	global_load_lds_dwordx4 v[246:247], off
	v_lshl_add_u64 v[246:247], s[2:3], 0, v[140:141]
	s_mov_b32 m0, s80
	s_nop 0
	global_load_lds_dwordx4 v[246:247], off
	s_waitcnt vmcnt(8)
	s_waitcnt lgkmcnt(0)
	s_barrier
	s_setprio 1
	s_waitcnt lgkmcnt(0)
	v_mfma_f32_16x16x32_bf16 v[134:137], v[58:61], v[174:177], v[134:137]
	v_mfma_f32_16x16x32_bf16 v[130:133], v[150:153], v[174:177], v[130:133]
	v_mfma_f32_16x16x32_bf16 v[118:121], v[58:61], v[184:187], v[118:121]
	v_mfma_f32_16x16x32_bf16 v[114:117], v[150:153], v[184:187], v[114:117]
	v_mfma_f32_16x16x32_bf16 v[102:105], v[58:61], v[214:217], v[102:105]
	v_mfma_f32_16x16x32_bf16 v[98:101], v[150:153], v[214:217], v[98:101]
	v_mfma_f32_16x16x32_bf16 v[86:89], v[58:61], v[232:235], v[86:89]
	v_mfma_f32_16x16x32_bf16 v[82:85], v[150:153], v[232:235], v[82:85]
	v_mfma_f32_16x16x32_bf16 v[134:137], v[62:65], v[180:183], v[134:137]
	v_mfma_f32_16x16x32_bf16 v[130:133], v[154:157], v[180:183], v[130:133]
	v_mfma_f32_16x16x32_bf16 v[118:121], v[62:65], v[188:191], v[118:121]
	v_mfma_f32_16x16x32_bf16 v[114:117], v[154:157], v[188:191], v[114:117]
	v_mfma_f32_16x16x32_bf16 v[102:105], v[62:65], v[228:231], v[102:105]
	v_mfma_f32_16x16x32_bf16 v[98:101], v[154:157], v[228:231], v[98:101]
	v_mfma_f32_16x16x32_bf16 v[86:89], v[62:65], v[236:239], v[86:89]
	v_mfma_f32_16x16x32_bf16 v[82:85], v[154:157], v[236:239], v[82:85]
	s_setprio 0
	s_setprio 1
	v_mfma_f32_16x16x32_bf16 v[126:129], v[158:161], v[174:177], v[126:129]
	v_mfma_f32_16x16x32_bf16 v[122:125], v[166:169], v[174:177], v[122:125]
	v_mfma_f32_16x16x32_bf16 v[110:113], v[158:161], v[184:187], v[110:113]
	v_mfma_f32_16x16x32_bf16 v[106:109], v[166:169], v[184:187], v[106:109]
	v_mfma_f32_16x16x32_bf16 v[94:97], v[158:161], v[214:217], v[94:97]
	v_mfma_f32_16x16x32_bf16 v[90:93], v[166:169], v[214:217], v[90:93]
	v_mfma_f32_16x16x32_bf16 v[78:81], v[158:161], v[232:235], v[78:81]
	v_mfma_f32_16x16x32_bf16 v[74:77], v[166:169], v[232:235], v[74:77]
	v_mfma_f32_16x16x32_bf16 v[126:129], v[162:165], v[180:183], v[126:129]
	v_mfma_f32_16x16x32_bf16 v[122:125], v[170:173], v[180:183], v[122:125]
	v_mfma_f32_16x16x32_bf16 v[110:113], v[162:165], v[188:191], v[110:113]
	v_mfma_f32_16x16x32_bf16 v[106:109], v[170:173], v[188:191], v[106:109]
	v_mfma_f32_16x16x32_bf16 v[94:97], v[162:165], v[228:231], v[94:97]
	v_mfma_f32_16x16x32_bf16 v[90:93], v[170:173], v[228:231], v[90:93]
	v_mfma_f32_16x16x32_bf16 v[78:81], v[162:165], v[236:239], v[78:81]
	v_mfma_f32_16x16x32_bf16 v[74:77], v[170:173], v[236:239], v[74:77]
	s_setprio 0
	s_barrier
	s_add_i32 s0, s0, s75
	v_lshl_add_u64 v[218:219], v[218:219], 0, s[52:53]
	s_mov_b32 m0, s0
	ds_read_b128 v[174:177], v179 offset:49152
	ds_read_b128 v[180:183], v179 offset:50176
	ds_read_b128 v[184:187], v179 offset:51200
	ds_read_b128 v[188:191], v179 offset:52224
	ds_read_b128 v[214:217], v179 offset:53248
	ds_read_b128 v[228:231], v179 offset:54272
	ds_read_b128 v[232:235], v179 offset:55296
	ds_read_b128 v[236:239], v179 offset:56320
	global_load_lds_dwordx4 v[218:219], off
	s_add_i32 m0, s0, 0x2000
	s_add_u32 s2, s38, 0x18080
	v_lshl_add_u64 v[218:219], v[240:241], 0, s[52:53]
	s_addc_u32 s3, s39, 0
	s_add_i32 s0, s45, s75
	global_load_lds_dwordx4 v[218:219], off
	v_lshl_add_u64 v[218:219], s[2:3], 0, v[142:143]
	s_mov_b32 m0, s0
	s_nop 0
	global_load_lds_dwordx4 v[218:219], off
	v_lshl_add_u64 v[218:219], s[2:3], 0, v[138:139]
	s_add_i32 m0, s0, 0x2000
	s_nop 0
	global_load_lds_dwordx4 v[218:219], off
	v_lshl_add_u64 v[218:219], v[242:243], 0, s[52:53]
	s_mov_b32 m0, s84
	s_nop 0
	global_load_lds_dwordx4 v[218:219], off
	v_lshl_add_u64 v[218:219], v[244:245], 0, s[52:53]
	s_mov_b32 m0, s85
	s_nop 0
	global_load_lds_dwordx4 v[218:219], off
	s_waitcnt vmcnt(8)
	s_waitcnt lgkmcnt(0)
	s_barrier
	s_setprio 1
	s_waitcnt lgkmcnt(0)
	v_mfma_f32_16x16x32_bf16 v[70:73], v[58:61], v[174:177], v[70:73]
	v_mfma_f32_16x16x32_bf16 v[66:69], v[150:153], v[174:177], v[66:69]
	v_mfma_f32_16x16x32_bf16 v[46:49], v[58:61], v[184:187], v[46:49]
	v_mfma_f32_16x16x32_bf16 v[42:45], v[150:153], v[184:187], v[42:45]
	v_mfma_f32_16x16x32_bf16 v[30:33], v[58:61], v[214:217], v[30:33]
	v_mfma_f32_16x16x32_bf16 v[26:29], v[150:153], v[214:217], v[26:29]
	v_mfma_f32_16x16x32_bf16 v[14:17], v[58:61], v[232:235], v[14:17]
	v_mfma_f32_16x16x32_bf16 v[10:13], v[150:153], v[232:235], v[10:13]
	v_mfma_f32_16x16x32_bf16 v[70:73], v[62:65], v[180:183], v[70:73]
	v_mfma_f32_16x16x32_bf16 v[66:69], v[154:157], v[180:183], v[66:69]
	v_mfma_f32_16x16x32_bf16 v[46:49], v[62:65], v[188:191], v[46:49]
	v_mfma_f32_16x16x32_bf16 v[42:45], v[154:157], v[188:191], v[42:45]
	v_mfma_f32_16x16x32_bf16 v[30:33], v[62:65], v[228:231], v[30:33]
	v_mfma_f32_16x16x32_bf16 v[26:29], v[154:157], v[228:231], v[26:29]
	v_mfma_f32_16x16x32_bf16 v[14:17], v[62:65], v[236:239], v[14:17]
	v_mfma_f32_16x16x32_bf16 v[10:13], v[154:157], v[236:239], v[10:13]
	s_setprio 0
	s_setprio 1
	v_mfma_f32_16x16x32_bf16 v[50:53], v[158:161], v[174:177], v[50:53]
	v_mfma_f32_16x16x32_bf16 v[62:65], v[162:165], v[180:183], v[50:53]
	v_mfma_f32_16x16x32_bf16 v[50:53], v[166:169], v[174:177], v[54:57]
	v_mfma_f32_16x16x32_bf16 v[38:41], v[158:161], v[184:187], v[38:41]
	v_mfma_f32_16x16x32_bf16 v[34:37], v[166:169], v[184:187], v[34:37]
	v_mfma_f32_16x16x32_bf16 v[22:25], v[158:161], v[214:217], v[22:25]
	v_mfma_f32_16x16x32_bf16 v[18:21], v[166:169], v[214:217], v[18:21]
	v_mfma_f32_16x16x32_bf16 v[6:9], v[158:161], v[232:235], v[6:9]
	v_mfma_f32_16x16x32_bf16 v[2:5], v[166:169], v[232:235], v[2:5]
	v_mfma_f32_16x16x32_bf16 v[58:61], v[170:173], v[180:183], v[50:53]
	v_mfma_f32_16x16x32_bf16 v[38:41], v[162:165], v[188:191], v[38:41]
	v_mfma_f32_16x16x32_bf16 v[34:37], v[170:173], v[188:191], v[34:37]
	v_mfma_f32_16x16x32_bf16 v[22:25], v[162:165], v[228:231], v[22:25]
	v_mfma_f32_16x16x32_bf16 v[18:21], v[170:173], v[228:231], v[18:21]
	v_mfma_f32_16x16x32_bf16 v[6:9], v[162:165], v[236:239], v[6:9]
	v_mfma_f32_16x16x32_bf16 v[2:5], v[170:173], v[236:239], v[2:5]
	s_setprio 0
	s_barrier
	s_add_i32 s44, s44, 2
	s_add_u32 s42, s42, 0x100
	s_addc_u32 s43, s43, 0
	s_cmp_gt_u32 s44, 3
	s_mov_b64 s[2:3], s[24:25]
	s_cbranch_scc0 .LBB0_268
	s_and_b64 vcc, exec, s[14:15]
	s_cbranch_vccz .LBB0_271
	s_barrier
.LBB0_271:
	s_lshl_b32 s0, s29, 8
	s_add_i32 s0, s0, s82
	v_and_or_b32 v0, v193, 15, s0
	v_bfe_u32 v218, v193, 4, 2
	s_lshl_b32 s0, s28, 3
	s_or_b32 s0, s0, s81
	s_mul_i32 s2, s0, 43
	s_lshr_b32 s2, s2, 7
	s_mul_i32 s2, s2, 3
	s_sub_i32 s0, s0, s2
	s_lshl_b32 s2, s28, 9
	s_lshl_b32 s24, s83, 1
	s_or_b32 s2, s2, s24
	v_lshl_or_b32 v219, v218, 4, s2
	v_mad_u32_u24 v219, v0, s47, v219
	s_mov_b32 vcc_lo, -1
	s_mov_b32 vcc_hi, 0xffff
	s_cmp_eq_u32 s0, 2
	s_cbranch_scc1 .Luq_r0
	s_cmp_eq_u32 s0, 1
	s_cbranch_scc1 .Luq_r1
	v_add_f32_e32 v194, v195, v194
	v_add_f32_e32 v196, v196, v197
	v_add_f32_e32 v198, v199, v198
	v_add_f32_e32 v200, v200, v201
	v_add_f32_e32 v202, v203, v202
	v_add_f32_e32 v204, v204, v205
	v_add_f32_e32 v206, v207, v206
	v_add_f32_e32 v208, v208, v209
	v_add_f32_e32 v194, v194, v196
	v_add_f32_e32 v198, v198, v200
	v_add_f32_e32 v202, v202, v204
	v_add_f32_e32 v206, v206, v208
	v_cndmask_b32_e32 v221, 0, v221, vcc
	v_cndmask_b32_e32 v222, 0, v222, vcc
	v_cndmask_b32_e32 v223, 0, v223, vcc
	v_cndmask_b32_e32 v224, 0, v224, vcc
	v_cndmask_b32_e32 v194, 0, v194, vcc
	v_cndmask_b32_e32 v198, 0, v198, vcc
	v_cndmask_b32_e32 v202, 0, v202, vcc
	v_cndmask_b32_e32 v206, 0, v206, vcc
	ds_swizzle_b32 v195, v221 offset:swizzle(SWAP,16)
	ds_swizzle_b32 v196, v222 offset:swizzle(SWAP,16)
	ds_swizzle_b32 v199, v223 offset:swizzle(SWAP,16)
	ds_swizzle_b32 v200, v224 offset:swizzle(SWAP,16)
	ds_swizzle_b32 v203, v194 offset:swizzle(SWAP,16)
	ds_swizzle_b32 v204, v198 offset:swizzle(SWAP,16)
	ds_swizzle_b32 v207, v202 offset:swizzle(SWAP,16)
	ds_swizzle_b32 v208, v206 offset:swizzle(SWAP,16)
	s_waitcnt lgkmcnt(0)
	v_add_f32_e32 v221, v221, v195
	v_add_f32_e32 v222, v222, v196
	v_add_f32_e32 v223, v223, v199
	v_add_f32_e32 v224, v224, v200
	v_add_f32_e32 v194, v194, v203
	v_add_f32_e32 v198, v198, v204
	v_add_f32_e32 v202, v202, v207
	v_add_f32_e32 v206, v206, v208
	v_mov_b32_e32 v197, v221
	v_mov_b32_e32 v201, v222
	v_mov_b32_e32 v205, v223
	v_mov_b32_e32 v209, v224
	v_mov_b32_e32 v240, v194
	v_mov_b32_e32 v241, v198
	v_mov_b32_e32 v242, v202
	v_mov_b32_e32 v243, v206
	v_permlane32_swap_b32_e32 v221, v197
	v_permlane32_swap_b32_e32 v222, v201
	v_permlane32_swap_b32_e32 v223, v205
	v_permlane32_swap_b32_e32 v224, v209
	v_permlane32_swap_b32_e32 v194, v240
	v_permlane32_swap_b32_e32 v198, v241
	v_permlane32_swap_b32_e32 v202, v242
	v_permlane32_swap_b32_e32 v206, v243
	v_add_f32_e32 v221, v221, v197
	v_add_f32_e32 v222, v222, v201
	v_add_f32_e32 v223, v223, v205
	v_add_f32_e32 v224, v224, v209
	v_add_f32_e32 v194, v194, v240
	v_add_f32_e32 v198, v198, v241
	v_add_f32_e32 v202, v202, v242
	v_add_f32_e32 v206, v206, v243
	v_fmamk_f32 v221, v221, 0x3b2aaaab, v192
	v_fmamk_f32 v222, v222, 0x3b2aaaab, v192
	v_fmamk_f32 v223, v223, 0x3b2aaaab, v192
	v_fmamk_f32 v224, v224, 0x3b2aaaab, v192
	v_fmamk_f32 v194, v194, 0x3b2aaaab, v192
	v_fmamk_f32 v198, v198, 0x3b2aaaab, v192
	v_fmamk_f32 v202, v202, 0x3b2aaaab, v192
	v_fmamk_f32 v206, v206, 0x3b2aaaab, v192
	v_rsq_f32_e32 v221, v221
	v_rsq_f32_e32 v222, v222
	v_rsq_f32_e32 v223, v223
	v_rsq_f32_e32 v224, v224
	v_rsq_f32_e32 v194, v194
	v_rsq_f32_e32 v198, v198
	v_rsq_f32_e32 v202, v202
	v_rsq_f32_e32 v206, v206
	v_mul_f32_e32 v221, 0x3e16c740, v221
	v_mul_f32_e32 v222, 0x3e16c740, v222
	v_mul_f32_e32 v223, 0x3e16c740, v223
	v_mul_f32_e32 v224, 0x3e16c740, v224
	v_mul_f32_e32 v194, 0x3e16c740, v194
	v_mul_f32_e32 v198, 0x3e16c740, v198
	v_mul_f32_e32 v202, 0x3e16c740, v202
	v_mul_f32_e32 v206, 0x3e16c740, v206
	v_pk_mul_f32 v[134:135], v[134:135], v[220:221] op_sel:[0,1] op_sel_hi:[1,1]
	v_pk_mul_f32 v[136:137], v[136:137], v[220:221] op_sel:[0,1] op_sel_hi:[1,1]
	v_pk_mul_f32 v[130:131], v[130:131], v[220:221] op_sel:[0,1] op_sel_hi:[1,1]
	v_pk_mul_f32 v[132:133], v[132:133], v[220:221] op_sel:[0,1] op_sel_hi:[1,1]
	v_pk_mul_f32 v[126:127], v[126:127], v[220:221] op_sel:[0,1] op_sel_hi:[1,1]
	v_pk_mul_f32 v[128:129], v[128:129], v[220:221] op_sel:[0,1] op_sel_hi:[1,1]
	v_pk_mul_f32 v[122:123], v[122:123], v[220:221] op_sel:[0,1] op_sel_hi:[1,1]
	v_pk_mul_f32 v[124:125], v[124:125], v[220:221] op_sel:[0,1] op_sel_hi:[1,1]
	v_pk_mul_f32 v[118:119], v[118:119], v[222:223] op_sel_hi:[1,0]
	v_pk_mul_f32 v[120:121], v[120:121], v[222:223] op_sel_hi:[1,0]
	v_pk_mul_f32 v[114:115], v[114:115], v[222:223] op_sel_hi:[1,0]
	v_pk_mul_f32 v[116:117], v[116:117], v[222:223] op_sel_hi:[1,0]
	v_pk_mul_f32 v[110:111], v[110:111], v[222:223] op_sel_hi:[1,0]
	v_pk_mul_f32 v[112:113], v[112:113], v[222:223] op_sel_hi:[1,0]
	v_pk_mul_f32 v[106:107], v[106:107], v[222:223] op_sel_hi:[1,0]
	v_pk_mul_f32 v[108:109], v[108:109], v[222:223] op_sel_hi:[1,0]
	v_pk_mul_f32 v[102:103], v[102:103], v[222:223] op_sel:[0,1] op_sel_hi:[1,1]
	v_pk_mul_f32 v[104:105], v[104:105], v[222:223] op_sel:[0,1] op_sel_hi:[1,1]
	v_pk_mul_f32 v[98:99], v[98:99], v[222:223] op_sel:[0,1] op_sel_hi:[1,1]
	v_pk_mul_f32 v[100:101], v[100:101], v[222:223] op_sel:[0,1] op_sel_hi:[1,1]
	v_pk_mul_f32 v[94:95], v[94:95], v[222:223] op_sel:[0,1] op_sel_hi:[1,1]
	v_pk_mul_f32 v[96:97], v[96:97], v[222:223] op_sel:[0,1] op_sel_hi:[1,1]
	v_pk_mul_f32 v[90:91], v[90:91], v[222:223] op_sel:[0,1] op_sel_hi:[1,1]
	v_pk_mul_f32 v[92:93], v[92:93], v[222:223] op_sel:[0,1] op_sel_hi:[1,1]
	v_pk_mul_f32 v[86:87], v[86:87], v[224:225] op_sel_hi:[1,0]
	v_pk_mul_f32 v[88:89], v[88:89], v[224:225] op_sel_hi:[1,0]
	v_pk_mul_f32 v[82:83], v[82:83], v[224:225] op_sel_hi:[1,0]
	v_pk_mul_f32 v[84:85], v[84:85], v[224:225] op_sel_hi:[1,0]
	v_pk_mul_f32 v[78:79], v[78:79], v[224:225] op_sel_hi:[1,0]
	v_pk_mul_f32 v[80:81], v[80:81], v[224:225] op_sel_hi:[1,0]
	v_pk_mul_f32 v[74:75], v[74:75], v[224:225] op_sel_hi:[1,0]
	v_pk_mul_f32 v[76:77], v[76:77], v[224:225] op_sel_hi:[1,0]
	v_pk_mul_f32 v[70:71], v[70:71], v[194:195] op_sel_hi:[1,0]
	v_pk_mul_f32 v[72:73], v[72:73], v[194:195] op_sel_hi:[1,0]
	v_pk_mul_f32 v[66:67], v[66:67], v[194:195] op_sel_hi:[1,0]
	v_pk_mul_f32 v[68:69], v[68:69], v[194:195] op_sel_hi:[1,0]
	v_pk_mul_f32 v[62:63], v[62:63], v[194:195] op_sel_hi:[1,0]
	v_pk_mul_f32 v[64:65], v[64:65], v[194:195] op_sel_hi:[1,0]
	v_pk_mul_f32 v[58:59], v[58:59], v[194:195] op_sel_hi:[1,0]
	v_pk_mul_f32 v[60:61], v[60:61], v[194:195] op_sel_hi:[1,0]
	v_pk_mul_f32 v[46:47], v[46:47], v[198:199] op_sel_hi:[1,0]
	v_pk_mul_f32 v[48:49], v[48:49], v[198:199] op_sel_hi:[1,0]
	v_pk_mul_f32 v[42:43], v[42:43], v[198:199] op_sel_hi:[1,0]
	v_pk_mul_f32 v[44:45], v[44:45], v[198:199] op_sel_hi:[1,0]
	v_pk_mul_f32 v[38:39], v[38:39], v[198:199] op_sel_hi:[1,0]
	v_pk_mul_f32 v[40:41], v[40:41], v[198:199] op_sel_hi:[1,0]
	v_pk_mul_f32 v[34:35], v[34:35], v[198:199] op_sel_hi:[1,0]
	v_pk_mul_f32 v[36:37], v[36:37], v[198:199] op_sel_hi:[1,0]
	v_pk_mul_f32 v[30:31], v[30:31], v[202:203] op_sel_hi:[1,0]
	v_pk_mul_f32 v[32:33], v[32:33], v[202:203] op_sel_hi:[1,0]
	v_pk_mul_f32 v[26:27], v[26:27], v[202:203] op_sel_hi:[1,0]
	v_pk_mul_f32 v[28:29], v[28:29], v[202:203] op_sel_hi:[1,0]
	v_pk_mul_f32 v[22:23], v[22:23], v[202:203] op_sel_hi:[1,0]
	v_pk_mul_f32 v[24:25], v[24:25], v[202:203] op_sel_hi:[1,0]
	v_pk_mul_f32 v[18:19], v[18:19], v[202:203] op_sel_hi:[1,0]
	v_pk_mul_f32 v[20:21], v[20:21], v[202:203] op_sel_hi:[1,0]
	v_pk_mul_f32 v[14:15], v[14:15], v[206:207] op_sel_hi:[1,0]
	v_pk_mul_f32 v[16:17], v[16:17], v[206:207] op_sel_hi:[1,0]
	v_pk_mul_f32 v[10:11], v[10:11], v[206:207] op_sel_hi:[1,0]
	v_pk_mul_f32 v[12:13], v[12:13], v[206:207] op_sel_hi:[1,0]
	v_pk_mul_f32 v[6:7], v[6:7], v[206:207] op_sel_hi:[1,0]
	v_pk_mul_f32 v[8:9], v[8:9], v[206:207] op_sel_hi:[1,0]
	v_pk_mul_f32 v[2:3], v[2:3], v[206:207] op_sel_hi:[1,0]
	v_pk_mul_f32 v[4:5], v[4:5], v[206:207] op_sel_hi:[1,0]
	v_cvt_pk_bf16_f32 v134, v134, v135
	v_cvt_pk_bf16_f32 v135, v136, v137
	v_cvt_pk_bf16_f32 v136, v130, v131
	v_cvt_pk_bf16_f32 v137, v132, v133
	v_add_u32_e32 v246, 0x0, v219
	global_store_dwordx4 v246, v[134:137], s[8:9]
	v_cvt_pk_bf16_f32 v126, v126, v127
	v_cvt_pk_bf16_f32 v127, v128, v129
	v_cvt_pk_bf16_f32 v128, v122, v123
	v_cvt_pk_bf16_f32 v129, v124, v125
	v_add_u32_e32 v247, 0x0, v219
	global_store_dwordx4 v247, v[126:129], s[8:9] offset:256
	v_cvt_pk_bf16_f32 v118, v118, v119
	v_cvt_pk_bf16_f32 v119, v120, v121
	v_cvt_pk_bf16_f32 v120, v114, v115
	v_cvt_pk_bf16_f32 v121, v116, v117
	v_add_u32_e32 v246, 0xc000, v219
	global_store_dwordx4 v246, v[118:121], s[8:9]
	v_cvt_pk_bf16_f32 v110, v110, v111
	v_cvt_pk_bf16_f32 v111, v112, v113
	v_cvt_pk_bf16_f32 v112, v106, v107
	v_cvt_pk_bf16_f32 v113, v108, v109
	v_add_u32_e32 v247, 0xc000, v219
	global_store_dwordx4 v247, v[110:113], s[8:9] offset:256
	v_cvt_pk_bf16_f32 v102, v102, v103
	v_cvt_pk_bf16_f32 v103, v104, v105
	v_cvt_pk_bf16_f32 v104, v98, v99
	v_cvt_pk_bf16_f32 v105, v100, v101
	v_add_u32_e32 v246, 0x18000, v219
	global_store_dwordx4 v246, v[102:105], s[8:9]
	v_cvt_pk_bf16_f32 v94, v94, v95
	v_cvt_pk_bf16_f32 v95, v96, v97
	v_cvt_pk_bf16_f32 v96, v90, v91
	v_cvt_pk_bf16_f32 v97, v92, v93
	v_add_u32_e32 v247, 0x18000, v219
	global_store_dwordx4 v247, v[94:97], s[8:9] offset:256
	v_cvt_pk_bf16_f32 v86, v86, v87
	v_cvt_pk_bf16_f32 v87, v88, v89
	v_cvt_pk_bf16_f32 v88, v82, v83
	v_cvt_pk_bf16_f32 v89, v84, v85
	v_add_u32_e32 v246, 0x24000, v219
	global_store_dwordx4 v246, v[86:89], s[8:9]
	v_cvt_pk_bf16_f32 v78, v78, v79
	v_cvt_pk_bf16_f32 v79, v80, v81
	v_cvt_pk_bf16_f32 v80, v74, v75
	v_cvt_pk_bf16_f32 v81, v76, v77
	v_add_u32_e32 v247, 0x24000, v219
	global_store_dwordx4 v247, v[78:81], s[8:9] offset:256
	v_cvt_pk_bf16_f32 v70, v70, v71
	v_cvt_pk_bf16_f32 v71, v72, v73
	v_cvt_pk_bf16_f32 v72, v66, v67
	v_cvt_pk_bf16_f32 v73, v68, v69
	v_add_u32_e32 v246, 0x60000, v219
	global_store_dwordx4 v246, v[70:73], s[8:9]
	v_cvt_pk_bf16_f32 v62, v62, v63
	v_cvt_pk_bf16_f32 v63, v64, v65
	v_cvt_pk_bf16_f32 v64, v58, v59
	v_cvt_pk_bf16_f32 v65, v60, v61
	v_add_u32_e32 v247, 0x60000, v219
	global_store_dwordx4 v247, v[62:65], s[8:9] offset:256
	v_cvt_pk_bf16_f32 v46, v46, v47
	v_cvt_pk_bf16_f32 v47, v48, v49
	v_cvt_pk_bf16_f32 v48, v42, v43
	v_cvt_pk_bf16_f32 v49, v44, v45
	v_add_u32_e32 v246, 0x6c000, v219
	global_store_dwordx4 v246, v[46:49], s[8:9]
	v_cvt_pk_bf16_f32 v38, v38, v39
	v_cvt_pk_bf16_f32 v39, v40, v41
	v_cvt_pk_bf16_f32 v40, v34, v35
	v_cvt_pk_bf16_f32 v41, v36, v37
	v_add_u32_e32 v247, 0x6c000, v219
	global_store_dwordx4 v247, v[38:41], s[8:9] offset:256
	v_cvt_pk_bf16_f32 v30, v30, v31
	v_cvt_pk_bf16_f32 v31, v32, v33
	v_cvt_pk_bf16_f32 v32, v26, v27
	v_cvt_pk_bf16_f32 v33, v28, v29
	v_add_u32_e32 v246, 0x78000, v219
	global_store_dwordx4 v246, v[30:33], s[8:9]
	v_cvt_pk_bf16_f32 v22, v22, v23
	v_cvt_pk_bf16_f32 v23, v24, v25
	v_cvt_pk_bf16_f32 v24, v18, v19
	v_cvt_pk_bf16_f32 v25, v20, v21
	v_add_u32_e32 v247, 0x78000, v219
	global_store_dwordx4 v247, v[22:25], s[8:9] offset:256
	v_cvt_pk_bf16_f32 v14, v14, v15
	v_cvt_pk_bf16_f32 v15, v16, v17
	v_cvt_pk_bf16_f32 v16, v10, v11
	v_cvt_pk_bf16_f32 v17, v12, v13
	v_add_u32_e32 v246, 0x84000, v219
	global_store_dwordx4 v246, v[14:17], s[8:9]
	v_cvt_pk_bf16_f32 v6, v6, v7
	v_cvt_pk_bf16_f32 v7, v8, v9
	v_cvt_pk_bf16_f32 v8, v2, v3
	v_cvt_pk_bf16_f32 v9, v4, v5
	v_add_u32_e32 v247, 0x84000, v219
	global_store_dwordx4 v247, v[6:9], s[8:9] offset:256
	s_branch .Luq_end
.Luq_r0:
	v_and_b32_e32 v246, 1, v218
	v_and_b32_e32 v247, 2, v218
	v_lshlrev_b32_e32 v244, 6, v0
	v_lshl_add_u32 v244, v246, 5, v244
	v_lshl_add_u32 v244, v247, 3, v244
	v_add_u32_e32 v245, 0x2000, v244
	global_load_dwordx4 v[228:231], v244, s[10:11]
	global_load_dwordx4 v[232:235], v244, s[12:13]
	global_load_dwordx4 v[236:239], v244, s[10:11] offset:1024
	global_load_dwordx4 v[50:53], v244, s[12:13] offset:1024
	global_load_dwordx4 v[54:57], v244, s[10:11] offset:2048
	global_load_dwordx4 v[184:187], v244, s[12:13] offset:2048
	global_load_dwordx4 v[188:191], v244, s[10:11] offset:3072
	global_load_dwordx4 v[214:217], v244, s[12:13] offset:3072
	global_load_dwordx4 v[150:153], v245, s[10:11]
	global_load_dwordx4 v[154:157], v245, s[12:13]
	global_load_dwordx4 v[158:161], v245, s[10:11] offset:1024
	global_load_dwordx4 v[162:165], v245, s[12:13] offset:1024
	global_load_dwordx4 v[166:169], v245, s[10:11] offset:2048
	global_load_dwordx4 v[170:173], v245, s[12:13] offset:2048
	global_load_dwordx4 v[174:177], v245, s[10:11] offset:3072
	global_load_dwordx4 v[180:183], v245, s[12:13] offset:3072
	v_add_f32_e32 v194, v195, v194
	v_add_f32_e32 v196, v196, v197
	v_add_f32_e32 v198, v199, v198
	v_add_f32_e32 v200, v200, v201
	v_add_f32_e32 v202, v203, v202
	v_add_f32_e32 v204, v204, v205
	v_add_f32_e32 v206, v207, v206
	v_add_f32_e32 v208, v208, v209
	v_add_f32_e32 v194, v194, v196
	v_add_f32_e32 v198, v198, v200
	v_add_f32_e32 v202, v202, v204
	v_add_f32_e32 v206, v206, v208
	v_cndmask_b32_e32 v221, 0, v221, vcc
	v_cndmask_b32_e32 v222, 0, v222, vcc
	v_cndmask_b32_e32 v223, 0, v223, vcc
	v_cndmask_b32_e32 v224, 0, v224, vcc
	v_cndmask_b32_e32 v194, 0, v194, vcc
	v_cndmask_b32_e32 v198, 0, v198, vcc
	v_cndmask_b32_e32 v202, 0, v202, vcc
	v_cndmask_b32_e32 v206, 0, v206, vcc
	ds_swizzle_b32 v195, v221 offset:swizzle(SWAP,16)
	ds_swizzle_b32 v196, v222 offset:swizzle(SWAP,16)
	ds_swizzle_b32 v199, v223 offset:swizzle(SWAP,16)
	ds_swizzle_b32 v200, v224 offset:swizzle(SWAP,16)
	ds_swizzle_b32 v203, v194 offset:swizzle(SWAP,16)
	ds_swizzle_b32 v204, v198 offset:swizzle(SWAP,16)
	ds_swizzle_b32 v207, v202 offset:swizzle(SWAP,16)
	ds_swizzle_b32 v208, v206 offset:swizzle(SWAP,16)
	s_waitcnt lgkmcnt(0)
	v_add_f32_e32 v221, v221, v195
	v_add_f32_e32 v222, v222, v196
	v_add_f32_e32 v223, v223, v199
	v_add_f32_e32 v224, v224, v200
	v_add_f32_e32 v194, v194, v203
	v_add_f32_e32 v198, v198, v204
	v_add_f32_e32 v202, v202, v207
	v_add_f32_e32 v206, v206, v208
	v_mov_b32_e32 v197, v221
	v_mov_b32_e32 v201, v222
	v_mov_b32_e32 v205, v223
	v_mov_b32_e32 v209, v224
	v_mov_b32_e32 v240, v194
	v_mov_b32_e32 v241, v198
	v_mov_b32_e32 v242, v202
	v_mov_b32_e32 v243, v206
	v_permlane32_swap_b32_e32 v221, v197
	v_permlane32_swap_b32_e32 v222, v201
	v_permlane32_swap_b32_e32 v223, v205
	v_permlane32_swap_b32_e32 v224, v209
	v_permlane32_swap_b32_e32 v194, v240
	v_permlane32_swap_b32_e32 v198, v241
	v_permlane32_swap_b32_e32 v202, v242
	v_permlane32_swap_b32_e32 v206, v243
	v_add_f32_e32 v221, v221, v197
	v_add_f32_e32 v222, v222, v201
	v_add_f32_e32 v223, v223, v205
	v_add_f32_e32 v224, v224, v209
	v_add_f32_e32 v194, v194, v240
	v_add_f32_e32 v198, v198, v241
	v_add_f32_e32 v202, v202, v242
	v_add_f32_e32 v206, v206, v243
	v_fmamk_f32 v221, v221, 0x3b2aaaab, v192
	v_fmamk_f32 v222, v222, 0x3b2aaaab, v192
	v_fmamk_f32 v223, v223, 0x3b2aaaab, v192
	v_fmamk_f32 v224, v224, 0x3b2aaaab, v192
	v_fmamk_f32 v194, v194, 0x3b2aaaab, v192
	v_fmamk_f32 v198, v198, 0x3b2aaaab, v192
	v_fmamk_f32 v202, v202, 0x3b2aaaab, v192
	v_fmamk_f32 v206, v206, 0x3b2aaaab, v192
	v_rsq_f32_e32 v221, v221
	v_rsq_f32_e32 v222, v222
	v_rsq_f32_e32 v223, v223
	v_rsq_f32_e32 v224, v224
	v_rsq_f32_e32 v194, v194
	v_rsq_f32_e32 v198, v198
	v_rsq_f32_e32 v202, v202
	v_rsq_f32_e32 v206, v206
	v_mul_f32_e32 v221, 0x3e16c740, v221
	v_mul_f32_e32 v222, 0x3e16c740, v222
	v_mul_f32_e32 v223, 0x3e16c740, v223
	v_mul_f32_e32 v224, 0x3e16c740, v224
	v_mul_f32_e32 v194, 0x3e16c740, v194
	v_mul_f32_e32 v198, 0x3e16c740, v198
	v_mul_f32_e32 v202, 0x3e16c740, v202
	v_mul_f32_e32 v206, 0x3e16c740, v206
	v_pk_mul_f32 v[134:135], v[134:135], v[220:221] op_sel:[0,1] op_sel_hi:[1,1]
	v_pk_mul_f32 v[136:137], v[136:137], v[220:221] op_sel:[0,1] op_sel_hi:[1,1]
	v_pk_mul_f32 v[130:131], v[130:131], v[220:221] op_sel:[0,1] op_sel_hi:[1,1]
	v_pk_mul_f32 v[132:133], v[132:133], v[220:221] op_sel:[0,1] op_sel_hi:[1,1]
	v_pk_mul_f32 v[126:127], v[126:127], v[220:221] op_sel:[0,1] op_sel_hi:[1,1]
	v_pk_mul_f32 v[128:129], v[128:129], v[220:221] op_sel:[0,1] op_sel_hi:[1,1]
	v_pk_mul_f32 v[122:123], v[122:123], v[220:221] op_sel:[0,1] op_sel_hi:[1,1]
	v_pk_mul_f32 v[124:125], v[124:125], v[220:221] op_sel:[0,1] op_sel_hi:[1,1]
	v_pk_mul_f32 v[118:119], v[118:119], v[222:223] op_sel_hi:[1,0]
	v_pk_mul_f32 v[120:121], v[120:121], v[222:223] op_sel_hi:[1,0]
	v_pk_mul_f32 v[114:115], v[114:115], v[222:223] op_sel_hi:[1,0]
	v_pk_mul_f32 v[116:117], v[116:117], v[222:223] op_sel_hi:[1,0]
	v_pk_mul_f32 v[110:111], v[110:111], v[222:223] op_sel_hi:[1,0]
	v_pk_mul_f32 v[112:113], v[112:113], v[222:223] op_sel_hi:[1,0]
	v_pk_mul_f32 v[106:107], v[106:107], v[222:223] op_sel_hi:[1,0]
	v_pk_mul_f32 v[108:109], v[108:109], v[222:223] op_sel_hi:[1,0]
	v_pk_mul_f32 v[102:103], v[102:103], v[222:223] op_sel:[0,1] op_sel_hi:[1,1]
	v_pk_mul_f32 v[104:105], v[104:105], v[222:223] op_sel:[0,1] op_sel_hi:[1,1]
	v_pk_mul_f32 v[98:99], v[98:99], v[222:223] op_sel:[0,1] op_sel_hi:[1,1]
	v_pk_mul_f32 v[100:101], v[100:101], v[222:223] op_sel:[0,1] op_sel_hi:[1,1]
	v_pk_mul_f32 v[94:95], v[94:95], v[222:223] op_sel:[0,1] op_sel_hi:[1,1]
	v_pk_mul_f32 v[96:97], v[96:97], v[222:223] op_sel:[0,1] op_sel_hi:[1,1]
	v_pk_mul_f32 v[90:91], v[90:91], v[222:223] op_sel:[0,1] op_sel_hi:[1,1]
	v_pk_mul_f32 v[92:93], v[92:93], v[222:223] op_sel:[0,1] op_sel_hi:[1,1]
	v_pk_mul_f32 v[86:87], v[86:87], v[224:225] op_sel_hi:[1,0]
	v_pk_mul_f32 v[88:89], v[88:89], v[224:225] op_sel_hi:[1,0]
	v_pk_mul_f32 v[82:83], v[82:83], v[224:225] op_sel_hi:[1,0]
	v_pk_mul_f32 v[84:85], v[84:85], v[224:225] op_sel_hi:[1,0]
	v_pk_mul_f32 v[78:79], v[78:79], v[224:225] op_sel_hi:[1,0]
	v_pk_mul_f32 v[80:81], v[80:81], v[224:225] op_sel_hi:[1,0]
	v_pk_mul_f32 v[74:75], v[74:75], v[224:225] op_sel_hi:[1,0]
	v_pk_mul_f32 v[76:77], v[76:77], v[224:225] op_sel_hi:[1,0]
	v_pk_mul_f32 v[70:71], v[70:71], v[194:195] op_sel_hi:[1,0]
	v_pk_mul_f32 v[72:73], v[72:73], v[194:195] op_sel_hi:[1,0]
	v_pk_mul_f32 v[66:67], v[66:67], v[194:195] op_sel_hi:[1,0]
	v_pk_mul_f32 v[68:69], v[68:69], v[194:195] op_sel_hi:[1,0]
	v_pk_mul_f32 v[62:63], v[62:63], v[194:195] op_sel_hi:[1,0]
	v_pk_mul_f32 v[64:65], v[64:65], v[194:195] op_sel_hi:[1,0]
	v_pk_mul_f32 v[58:59], v[58:59], v[194:195] op_sel_hi:[1,0]
	v_pk_mul_f32 v[60:61], v[60:61], v[194:195] op_sel_hi:[1,0]
	v_pk_mul_f32 v[46:47], v[46:47], v[198:199] op_sel_hi:[1,0]
	v_pk_mul_f32 v[48:49], v[48:49], v[198:199] op_sel_hi:[1,0]
	v_pk_mul_f32 v[42:43], v[42:43], v[198:199] op_sel_hi:[1,0]
	v_pk_mul_f32 v[44:45], v[44:45], v[198:199] op_sel_hi:[1,0]
	v_pk_mul_f32 v[38:39], v[38:39], v[198:199] op_sel_hi:[1,0]
	v_pk_mul_f32 v[40:41], v[40:41], v[198:199] op_sel_hi:[1,0]
	v_pk_mul_f32 v[34:35], v[34:35], v[198:199] op_sel_hi:[1,0]
	v_pk_mul_f32 v[36:37], v[36:37], v[198:199] op_sel_hi:[1,0]
	v_pk_mul_f32 v[30:31], v[30:31], v[202:203] op_sel_hi:[1,0]
	v_pk_mul_f32 v[32:33], v[32:33], v[202:203] op_sel_hi:[1,0]
	v_pk_mul_f32 v[26:27], v[26:27], v[202:203] op_sel_hi:[1,0]
	v_pk_mul_f32 v[28:29], v[28:29], v[202:203] op_sel_hi:[1,0]
	v_pk_mul_f32 v[22:23], v[22:23], v[202:203] op_sel_hi:[1,0]
	v_pk_mul_f32 v[24:25], v[24:25], v[202:203] op_sel_hi:[1,0]
	v_pk_mul_f32 v[18:19], v[18:19], v[202:203] op_sel_hi:[1,0]
	v_pk_mul_f32 v[20:21], v[20:21], v[202:203] op_sel_hi:[1,0]
	v_pk_mul_f32 v[14:15], v[14:15], v[206:207] op_sel_hi:[1,0]
	v_pk_mul_f32 v[16:17], v[16:17], v[206:207] op_sel_hi:[1,0]
	v_pk_mul_f32 v[10:11], v[10:11], v[206:207] op_sel_hi:[1,0]
	v_pk_mul_f32 v[12:13], v[12:13], v[206:207] op_sel_hi:[1,0]
	v_pk_mul_f32 v[6:7], v[6:7], v[206:207] op_sel_hi:[1,0]
	v_pk_mul_f32 v[8:9], v[8:9], v[206:207] op_sel_hi:[1,0]
	v_pk_mul_f32 v[2:3], v[2:3], v[206:207] op_sel_hi:[1,0]
	v_pk_mul_f32 v[4:5], v[4:5], v[206:207] op_sel_hi:[1,0]
	v_cvt_pk_bf16_f32 v126, v126, v127
	v_cvt_pk_bf16_f32 v127, v128, v129
	v_cvt_pk_bf16_f32 v128, v122, v123
	v_cvt_pk_bf16_f32 v129, v124, v125
	v_add_u32_e32 v246, 0x0, v219
	global_store_dwordx4 v246, v[126:129], s[8:9] offset:256
	v_cvt_pk_bf16_f32 v110, v110, v111
	v_cvt_pk_bf16_f32 v111, v112, v113
	v_cvt_pk_bf16_f32 v112, v106, v107
	v_cvt_pk_bf16_f32 v113, v108, v109
	v_add_u32_e32 v247, 0xc000, v219
	global_store_dwordx4 v247, v[110:113], s[8:9] offset:256
	v_cvt_pk_bf16_f32 v94, v94, v95
	v_cvt_pk_bf16_f32 v95, v96, v97
	v_cvt_pk_bf16_f32 v96, v90, v91
	v_cvt_pk_bf16_f32 v97, v92, v93
	v_add_u32_e32 v246, 0x18000, v219
	global_store_dwordx4 v246, v[94:97], s[8:9] offset:256
	v_cvt_pk_bf16_f32 v78, v78, v79
	v_cvt_pk_bf16_f32 v79, v80, v81
	v_cvt_pk_bf16_f32 v80, v74, v75
	v_cvt_pk_bf16_f32 v81, v76, v77
	v_add_u32_e32 v247, 0x24000, v219
	global_store_dwordx4 v247, v[78:81], s[8:9] offset:256
	v_cvt_pk_bf16_f32 v62, v62, v63
	v_cvt_pk_bf16_f32 v63, v64, v65
	v_cvt_pk_bf16_f32 v64, v58, v59
	v_cvt_pk_bf16_f32 v65, v60, v61
	v_add_u32_e32 v246, 0x60000, v219
	global_store_dwordx4 v246, v[62:65], s[8:9] offset:256
	v_cvt_pk_bf16_f32 v38, v38, v39
	v_cvt_pk_bf16_f32 v39, v40, v41
	v_cvt_pk_bf16_f32 v40, v34, v35
	v_cvt_pk_bf16_f32 v41, v36, v37
	v_add_u32_e32 v247, 0x6c000, v219
	global_store_dwordx4 v247, v[38:41], s[8:9] offset:256
	v_cvt_pk_bf16_f32 v22, v22, v23
	v_cvt_pk_bf16_f32 v23, v24, v25
	v_cvt_pk_bf16_f32 v24, v18, v19
	v_cvt_pk_bf16_f32 v25, v20, v21
	v_add_u32_e32 v246, 0x78000, v219
	global_store_dwordx4 v246, v[22:25], s[8:9] offset:256
	v_cvt_pk_bf16_f32 v6, v6, v7
	v_cvt_pk_bf16_f32 v7, v8, v9
	v_cvt_pk_bf16_f32 v8, v2, v3
	v_cvt_pk_bf16_f32 v9, v4, v5
	v_add_u32_e32 v247, 0x84000, v219
	global_store_dwordx4 v247, v[6:9], s[8:9] offset:256
	s_waitcnt vmcnt(20)
	v_permlane32_swap_b32_e32 v134, v130
	v_permlane32_swap_b32_e32 v135, v131
	v_permlane32_swap_b32_e32 v136, v132
	v_permlane32_swap_b32_e32 v137, v133
	v_permlane32_swap_b32_e32 v118, v114
	v_permlane32_swap_b32_e32 v119, v115
	v_permlane32_swap_b32_e32 v120, v116
	v_permlane32_swap_b32_e32 v121, v117
	v_pk_mul_f32 v[122:123], v[134:135], v[228:229]
	v_pk_mul_f32 v[124:125], v[136:137], v[230:231]
	v_pk_mul_f32 v[106:107], v[118:119], v[236:237]
	v_pk_mul_f32 v[108:109], v[120:121], v[238:239]
	v_pk_fma_f32 v[122:123], v[130:131], v[232:233], v[122:123] neg_lo:[1,0,0] neg_hi:[1,0,0]
	v_pk_fma_f32 v[124:125], v[132:133], v[234:235], v[124:125] neg_lo:[1,0,0] neg_hi:[1,0,0]
	v_pk_fma_f32 v[106:107], v[114:115], v[50:51], v[106:107] neg_lo:[1,0,0] neg_hi:[1,0,0]
	v_pk_fma_f32 v[108:109], v[116:117], v[52:53], v[108:109] neg_lo:[1,0,0] neg_hi:[1,0,0]
	v_pk_mul_f32 v[130:131], v[130:131], v[228:229]
	v_pk_mul_f32 v[132:133], v[132:133], v[230:231]
	v_pk_mul_f32 v[114:115], v[114:115], v[236:237]
	v_pk_mul_f32 v[116:117], v[116:117], v[238:239]
	v_pk_fma_f32 v[130:131], v[134:135], v[232:233], v[130:131]
	v_pk_fma_f32 v[132:133], v[136:137], v[234:235], v[132:133]
	v_pk_fma_f32 v[114:115], v[118:119], v[50:51], v[114:115]
	v_pk_fma_f32 v[116:117], v[120:121], v[52:53], v[116:117]
	v_permlane32_swap_b32_e32 v122, v130
	v_permlane32_swap_b32_e32 v123, v131
	v_permlane32_swap_b32_e32 v124, v132
	v_permlane32_swap_b32_e32 v125, v133
	v_permlane32_swap_b32_e32 v106, v114
	v_permlane32_swap_b32_e32 v107, v115
	v_permlane32_swap_b32_e32 v108, v116
	v_permlane32_swap_b32_e32 v109, v117
	v_cvt_pk_bf16_f32 v134, v122, v123
	v_cvt_pk_bf16_f32 v135, v124, v125
	v_cvt_pk_bf16_f32 v136, v130, v131
	v_cvt_pk_bf16_f32 v137, v132, v133
	v_add_u32_e32 v246, 0x0, v219
	global_store_dwordx4 v246, v[134:137], s[8:9]
	v_cvt_pk_bf16_f32 v118, v106, v107
	v_cvt_pk_bf16_f32 v119, v108, v109
	v_cvt_pk_bf16_f32 v120, v114, v115
	v_cvt_pk_bf16_f32 v121, v116, v117
	v_add_u32_e32 v247, 0xc000, v219
	global_store_dwordx4 v247, v[118:121], s[8:9]
	s_waitcnt vmcnt(18)
	v_permlane32_swap_b32_e32 v102, v98
	v_permlane32_swap_b32_e32 v103, v99
	v_permlane32_swap_b32_e32 v104, v100
	v_permlane32_swap_b32_e32 v105, v101
	v_permlane32_swap_b32_e32 v86, v82
	v_permlane32_swap_b32_e32 v87, v83
	v_permlane32_swap_b32_e32 v88, v84
	v_permlane32_swap_b32_e32 v89, v85
	v_pk_mul_f32 v[90:91], v[102:103], v[54:55]
	v_pk_mul_f32 v[92:93], v[104:105], v[56:57]
	v_pk_mul_f32 v[74:75], v[86:87], v[188:189]
	v_pk_mul_f32 v[76:77], v[88:89], v[190:191]
	v_pk_fma_f32 v[90:91], v[98:99], v[184:185], v[90:91] neg_lo:[1,0,0] neg_hi:[1,0,0]
	v_pk_fma_f32 v[92:93], v[100:101], v[186:187], v[92:93] neg_lo:[1,0,0] neg_hi:[1,0,0]
	v_pk_fma_f32 v[74:75], v[82:83], v[214:215], v[74:75] neg_lo:[1,0,0] neg_hi:[1,0,0]
	v_pk_fma_f32 v[76:77], v[84:85], v[216:217], v[76:77] neg_lo:[1,0,0] neg_hi:[1,0,0]
	v_pk_mul_f32 v[98:99], v[98:99], v[54:55]
	v_pk_mul_f32 v[100:101], v[100:101], v[56:57]
	v_pk_mul_f32 v[82:83], v[82:83], v[188:189]
	v_pk_mul_f32 v[84:85], v[84:85], v[190:191]
	v_pk_fma_f32 v[98:99], v[102:103], v[184:185], v[98:99]
	v_pk_fma_f32 v[100:101], v[104:105], v[186:187], v[100:101]
	v_pk_fma_f32 v[82:83], v[86:87], v[214:215], v[82:83]
	v_pk_fma_f32 v[84:85], v[88:89], v[216:217], v[84:85]
	v_permlane32_swap_b32_e32 v90, v98
	v_permlane32_swap_b32_e32 v91, v99
	v_permlane32_swap_b32_e32 v92, v100
	v_permlane32_swap_b32_e32 v93, v101
	v_permlane32_swap_b32_e32 v74, v82
	v_permlane32_swap_b32_e32 v75, v83
	v_permlane32_swap_b32_e32 v76, v84
	v_permlane32_swap_b32_e32 v77, v85
	v_cvt_pk_bf16_f32 v102, v90, v91
	v_cvt_pk_bf16_f32 v103, v92, v93
	v_cvt_pk_bf16_f32 v104, v98, v99
	v_cvt_pk_bf16_f32 v105, v100, v101
	v_add_u32_e32 v246, 0x18000, v219
	global_store_dwordx4 v246, v[102:105], s[8:9]
	v_cvt_pk_bf16_f32 v86, v74, v75
	v_cvt_pk_bf16_f32 v87, v76, v77
	v_cvt_pk_bf16_f32 v88, v82, v83
	v_cvt_pk_bf16_f32 v89, v84, v85
	v_add_u32_e32 v247, 0x24000, v219
	global_store_dwordx4 v247, v[86:89], s[8:9]
	s_waitcnt vmcnt(16)
	v_permlane32_swap_b32_e32 v70, v66
	v_permlane32_swap_b32_e32 v71, v67
	v_permlane32_swap_b32_e32 v72, v68
	v_permlane32_swap_b32_e32 v73, v69
	v_permlane32_swap_b32_e32 v46, v42
	v_permlane32_swap_b32_e32 v47, v43
	v_permlane32_swap_b32_e32 v48, v44
	v_permlane32_swap_b32_e32 v49, v45
	v_pk_mul_f32 v[58:59], v[70:71], v[150:151]
	v_pk_mul_f32 v[60:61], v[72:73], v[152:153]
	v_pk_mul_f32 v[34:35], v[46:47], v[158:159]
	v_pk_mul_f32 v[36:37], v[48:49], v[160:161]
	v_pk_fma_f32 v[58:59], v[66:67], v[154:155], v[58:59] neg_lo:[1,0,0] neg_hi:[1,0,0]
	v_pk_fma_f32 v[60:61], v[68:69], v[156:157], v[60:61] neg_lo:[1,0,0] neg_hi:[1,0,0]
	v_pk_fma_f32 v[34:35], v[42:43], v[162:163], v[34:35] neg_lo:[1,0,0] neg_hi:[1,0,0]
	v_pk_fma_f32 v[36:37], v[44:45], v[164:165], v[36:37] neg_lo:[1,0,0] neg_hi:[1,0,0]
	v_pk_mul_f32 v[66:67], v[66:67], v[150:151]
	v_pk_mul_f32 v[68:69], v[68:69], v[152:153]
	v_pk_mul_f32 v[42:43], v[42:43], v[158:159]
	v_pk_mul_f32 v[44:45], v[44:45], v[160:161]
	v_pk_fma_f32 v[66:67], v[70:71], v[154:155], v[66:67]
	v_pk_fma_f32 v[68:69], v[72:73], v[156:157], v[68:69]
	v_pk_fma_f32 v[42:43], v[46:47], v[162:163], v[42:43]
	v_pk_fma_f32 v[44:45], v[48:49], v[164:165], v[44:45]
	v_permlane32_swap_b32_e32 v58, v66
	v_permlane32_swap_b32_e32 v59, v67
	v_permlane32_swap_b32_e32 v60, v68
	v_permlane32_swap_b32_e32 v61, v69
	v_permlane32_swap_b32_e32 v34, v42
	v_permlane32_swap_b32_e32 v35, v43
	v_permlane32_swap_b32_e32 v36, v44
	v_permlane32_swap_b32_e32 v37, v45
	v_cvt_pk_bf16_f32 v70, v58, v59
	v_cvt_pk_bf16_f32 v71, v60, v61
	v_cvt_pk_bf16_f32 v72, v66, v67
	v_cvt_pk_bf16_f32 v73, v68, v69
	v_add_u32_e32 v246, 0x60000, v219
	global_store_dwordx4 v246, v[70:73], s[8:9]
	v_cvt_pk_bf16_f32 v46, v34, v35
	v_cvt_pk_bf16_f32 v47, v36, v37
	v_cvt_pk_bf16_f32 v48, v42, v43
	v_cvt_pk_bf16_f32 v49, v44, v45
	v_add_u32_e32 v247, 0x6c000, v219
	global_store_dwordx4 v247, v[46:49], s[8:9]
	s_waitcnt vmcnt(14)
	v_permlane32_swap_b32_e32 v30, v26
	v_permlane32_swap_b32_e32 v31, v27
	v_permlane32_swap_b32_e32 v32, v28
	v_permlane32_swap_b32_e32 v33, v29
	v_permlane32_swap_b32_e32 v14, v10
	v_permlane32_swap_b32_e32 v15, v11
	v_permlane32_swap_b32_e32 v16, v12
	v_permlane32_swap_b32_e32 v17, v13
	v_pk_mul_f32 v[18:19], v[30:31], v[166:167]
	v_pk_mul_f32 v[20:21], v[32:33], v[168:169]
	v_pk_mul_f32 v[2:3], v[14:15], v[174:175]
	v_pk_mul_f32 v[4:5], v[16:17], v[176:177]
	v_pk_fma_f32 v[18:19], v[26:27], v[170:171], v[18:19] neg_lo:[1,0,0] neg_hi:[1,0,0]
	v_pk_fma_f32 v[20:21], v[28:29], v[172:173], v[20:21] neg_lo:[1,0,0] neg_hi:[1,0,0]
	v_pk_fma_f32 v[2:3], v[10:11], v[180:181], v[2:3] neg_lo:[1,0,0] neg_hi:[1,0,0]
	v_pk_fma_f32 v[4:5], v[12:13], v[182:183], v[4:5] neg_lo:[1,0,0] neg_hi:[1,0,0]
	v_pk_mul_f32 v[26:27], v[26:27], v[166:167]
	v_pk_mul_f32 v[28:29], v[28:29], v[168:169]
	v_pk_mul_f32 v[10:11], v[10:11], v[174:175]
	v_pk_mul_f32 v[12:13], v[12:13], v[176:177]
	v_pk_fma_f32 v[26:27], v[30:31], v[170:171], v[26:27]
	v_pk_fma_f32 v[28:29], v[32:33], v[172:173], v[28:29]
	v_pk_fma_f32 v[10:11], v[14:15], v[180:181], v[10:11]
	v_pk_fma_f32 v[12:13], v[16:17], v[182:183], v[12:13]
	v_permlane32_swap_b32_e32 v18, v26
	v_permlane32_swap_b32_e32 v19, v27
	v_permlane32_swap_b32_e32 v20, v28
	v_permlane32_swap_b32_e32 v21, v29
	v_permlane32_swap_b32_e32 v2, v10
	v_permlane32_swap_b32_e32 v3, v11
	v_permlane32_swap_b32_e32 v4, v12
	v_permlane32_swap_b32_e32 v5, v13
	v_cvt_pk_bf16_f32 v30, v18, v19
	v_cvt_pk_bf16_f32 v31, v20, v21
	v_cvt_pk_bf16_f32 v32, v26, v27
	v_cvt_pk_bf16_f32 v33, v28, v29
	v_add_u32_e32 v246, 0x78000, v219
	global_store_dwordx4 v246, v[30:33], s[8:9]
	v_cvt_pk_bf16_f32 v14, v2, v3
	v_cvt_pk_bf16_f32 v15, v4, v5
	v_cvt_pk_bf16_f32 v16, v10, v11
	v_cvt_pk_bf16_f32 v17, v12, v13
	v_add_u32_e32 v247, 0x84000, v219
	global_store_dwordx4 v247, v[14:17], s[8:9]
	s_branch .Luq_end
.Luq_r1:
	v_and_b32_e32 v246, 1, v218
	v_and_b32_e32 v247, 2, v218
	v_lshlrev_b32_e32 v244, 6, v0
	v_lshl_add_u32 v244, v246, 5, v244
	v_lshl_add_u32 v244, v247, 3, v244
	v_add_u32_e32 v245, 0x2000, v244
	global_load_dwordx4 v[228:231], v244, s[10:11]
	global_load_dwordx4 v[232:235], v244, s[12:13]
	global_load_dwordx4 v[236:239], v244, s[10:11] offset:1024
	global_load_dwordx4 v[50:53], v244, s[12:13] offset:1024
	global_load_dwordx4 v[54:57], v244, s[10:11] offset:2048
	global_load_dwordx4 v[184:187], v244, s[12:13] offset:2048
	global_load_dwordx4 v[188:191], v244, s[10:11] offset:3072
	global_load_dwordx4 v[214:217], v244, s[12:13] offset:3072
	global_load_dwordx4 v[150:153], v245, s[10:11]
	global_load_dwordx4 v[154:157], v245, s[12:13]
	global_load_dwordx4 v[158:161], v245, s[10:11] offset:1024
	global_load_dwordx4 v[162:165], v245, s[12:13] offset:1024
	global_load_dwordx4 v[166:169], v245, s[10:11] offset:2048
	global_load_dwordx4 v[170:173], v245, s[12:13] offset:2048
	global_load_dwordx4 v[174:177], v245, s[10:11] offset:3072
	global_load_dwordx4 v[180:183], v245, s[12:13] offset:3072
	v_add_f32_e32 v194, v195, v194
	v_add_f32_e32 v196, v196, v197
	v_add_f32_e32 v198, v199, v198
	v_add_f32_e32 v200, v200, v201
	v_add_f32_e32 v202, v203, v202
	v_add_f32_e32 v204, v204, v205
	v_add_f32_e32 v206, v207, v206
	v_add_f32_e32 v208, v208, v209
	v_add_f32_e32 v194, v194, v196
	v_add_f32_e32 v198, v198, v200
	v_add_f32_e32 v202, v202, v204
	v_add_f32_e32 v206, v206, v208
	v_cndmask_b32_e32 v221, 0, v221, vcc
	v_cndmask_b32_e32 v222, 0, v222, vcc
	v_cndmask_b32_e32 v223, 0, v223, vcc
	v_cndmask_b32_e32 v224, 0, v224, vcc
	v_cndmask_b32_e32 v194, 0, v194, vcc
	v_cndmask_b32_e32 v198, 0, v198, vcc
	v_cndmask_b32_e32 v202, 0, v202, vcc
	v_cndmask_b32_e32 v206, 0, v206, vcc
	ds_swizzle_b32 v195, v221 offset:swizzle(SWAP,16)
	ds_swizzle_b32 v196, v222 offset:swizzle(SWAP,16)
	ds_swizzle_b32 v199, v223 offset:swizzle(SWAP,16)
	ds_swizzle_b32 v200, v224 offset:swizzle(SWAP,16)
	ds_swizzle_b32 v203, v194 offset:swizzle(SWAP,16)
	ds_swizzle_b32 v204, v198 offset:swizzle(SWAP,16)
	ds_swizzle_b32 v207, v202 offset:swizzle(SWAP,16)
	ds_swizzle_b32 v208, v206 offset:swizzle(SWAP,16)
	s_waitcnt lgkmcnt(0)
	v_add_f32_e32 v221, v221, v195
	v_add_f32_e32 v222, v222, v196
	v_add_f32_e32 v223, v223, v199
	v_add_f32_e32 v224, v224, v200
	v_add_f32_e32 v194, v194, v203
	v_add_f32_e32 v198, v198, v204
	v_add_f32_e32 v202, v202, v207
	v_add_f32_e32 v206, v206, v208
	v_mov_b32_e32 v197, v221
	v_mov_b32_e32 v201, v222
	v_mov_b32_e32 v205, v223
	v_mov_b32_e32 v209, v224
	v_mov_b32_e32 v240, v194
	v_mov_b32_e32 v241, v198
	v_mov_b32_e32 v242, v202
	v_mov_b32_e32 v243, v206
	v_permlane32_swap_b32_e32 v221, v197
	v_permlane32_swap_b32_e32 v222, v201
	v_permlane32_swap_b32_e32 v223, v205
	v_permlane32_swap_b32_e32 v224, v209
	v_permlane32_swap_b32_e32 v194, v240
	v_permlane32_swap_b32_e32 v198, v241
	v_permlane32_swap_b32_e32 v202, v242
	v_permlane32_swap_b32_e32 v206, v243
	v_add_f32_e32 v221, v221, v197
	v_add_f32_e32 v222, v222, v201
	v_add_f32_e32 v223, v223, v205
	v_add_f32_e32 v224, v224, v209
	v_add_f32_e32 v194, v194, v240
	v_add_f32_e32 v198, v198, v241
	v_add_f32_e32 v202, v202, v242
	v_add_f32_e32 v206, v206, v243
	v_fmamk_f32 v221, v221, 0x3b2aaaab, v192
	v_fmamk_f32 v222, v222, 0x3b2aaaab, v192
	v_fmamk_f32 v223, v223, 0x3b2aaaab, v192
	v_fmamk_f32 v224, v224, 0x3b2aaaab, v192
	v_fmamk_f32 v194, v194, 0x3b2aaaab, v192
	v_fmamk_f32 v198, v198, 0x3b2aaaab, v192
	v_fmamk_f32 v202, v202, 0x3b2aaaab, v192
	v_fmamk_f32 v206, v206, 0x3b2aaaab, v192
	v_rsq_f32_e32 v221, v221
	v_rsq_f32_e32 v222, v222
	v_rsq_f32_e32 v223, v223
	v_rsq_f32_e32 v224, v224
	v_rsq_f32_e32 v194, v194
	v_rsq_f32_e32 v198, v198
	v_rsq_f32_e32 v202, v202
	v_rsq_f32_e32 v206, v206
	v_mul_f32_e32 v221, 0x3e16c740, v221
	v_mul_f32_e32 v222, 0x3e16c740, v222
	v_mul_f32_e32 v223, 0x3e16c740, v223
	v_mul_f32_e32 v224, 0x3e16c740, v224
	v_mul_f32_e32 v194, 0x3e16c740, v194
	v_mul_f32_e32 v198, 0x3e16c740, v198
	v_mul_f32_e32 v202, 0x3e16c740, v202
	v_mul_f32_e32 v206, 0x3e16c740, v206
	v_pk_mul_f32 v[134:135], v[134:135], v[220:221] op_sel:[0,1] op_sel_hi:[1,1]
	v_pk_mul_f32 v[136:137], v[136:137], v[220:221] op_sel:[0,1] op_sel_hi:[1,1]
	v_pk_mul_f32 v[130:131], v[130:131], v[220:221] op_sel:[0,1] op_sel_hi:[1,1]
	v_pk_mul_f32 v[132:133], v[132:133], v[220:221] op_sel:[0,1] op_sel_hi:[1,1]
	v_pk_mul_f32 v[126:127], v[126:127], v[220:221] op_sel:[0,1] op_sel_hi:[1,1]
	v_pk_mul_f32 v[128:129], v[128:129], v[220:221] op_sel:[0,1] op_sel_hi:[1,1]
	v_pk_mul_f32 v[122:123], v[122:123], v[220:221] op_sel:[0,1] op_sel_hi:[1,1]
	v_pk_mul_f32 v[124:125], v[124:125], v[220:221] op_sel:[0,1] op_sel_hi:[1,1]
	v_pk_mul_f32 v[118:119], v[118:119], v[222:223] op_sel_hi:[1,0]
	v_pk_mul_f32 v[120:121], v[120:121], v[222:223] op_sel_hi:[1,0]
	v_pk_mul_f32 v[114:115], v[114:115], v[222:223] op_sel_hi:[1,0]
	v_pk_mul_f32 v[116:117], v[116:117], v[222:223] op_sel_hi:[1,0]
	v_pk_mul_f32 v[110:111], v[110:111], v[222:223] op_sel_hi:[1,0]
	v_pk_mul_f32 v[112:113], v[112:113], v[222:223] op_sel_hi:[1,0]
	v_pk_mul_f32 v[106:107], v[106:107], v[222:223] op_sel_hi:[1,0]
	v_pk_mul_f32 v[108:109], v[108:109], v[222:223] op_sel_hi:[1,0]
	v_pk_mul_f32 v[102:103], v[102:103], v[222:223] op_sel:[0,1] op_sel_hi:[1,1]
	v_pk_mul_f32 v[104:105], v[104:105], v[222:223] op_sel:[0,1] op_sel_hi:[1,1]
	v_pk_mul_f32 v[98:99], v[98:99], v[222:223] op_sel:[0,1] op_sel_hi:[1,1]
	v_pk_mul_f32 v[100:101], v[100:101], v[222:223] op_sel:[0,1] op_sel_hi:[1,1]
	v_pk_mul_f32 v[94:95], v[94:95], v[222:223] op_sel:[0,1] op_sel_hi:[1,1]
	v_pk_mul_f32 v[96:97], v[96:97], v[222:223] op_sel:[0,1] op_sel_hi:[1,1]
	v_pk_mul_f32 v[90:91], v[90:91], v[222:223] op_sel:[0,1] op_sel_hi:[1,1]
	v_pk_mul_f32 v[92:93], v[92:93], v[222:223] op_sel:[0,1] op_sel_hi:[1,1]
	v_pk_mul_f32 v[86:87], v[86:87], v[224:225] op_sel_hi:[1,0]
	v_pk_mul_f32 v[88:89], v[88:89], v[224:225] op_sel_hi:[1,0]
	v_pk_mul_f32 v[82:83], v[82:83], v[224:225] op_sel_hi:[1,0]
	v_pk_mul_f32 v[84:85], v[84:85], v[224:225] op_sel_hi:[1,0]
	v_pk_mul_f32 v[78:79], v[78:79], v[224:225] op_sel_hi:[1,0]
	v_pk_mul_f32 v[80:81], v[80:81], v[224:225] op_sel_hi:[1,0]
	v_pk_mul_f32 v[74:75], v[74:75], v[224:225] op_sel_hi:[1,0]
	v_pk_mul_f32 v[76:77], v[76:77], v[224:225] op_sel_hi:[1,0]
	v_pk_mul_f32 v[70:71], v[70:71], v[194:195] op_sel_hi:[1,0]
	v_pk_mul_f32 v[72:73], v[72:73], v[194:195] op_sel_hi:[1,0]
	v_pk_mul_f32 v[66:67], v[66:67], v[194:195] op_sel_hi:[1,0]
	v_pk_mul_f32 v[68:69], v[68:69], v[194:195] op_sel_hi:[1,0]
	v_pk_mul_f32 v[62:63], v[62:63], v[194:195] op_sel_hi:[1,0]
	v_pk_mul_f32 v[64:65], v[64:65], v[194:195] op_sel_hi:[1,0]
	v_pk_mul_f32 v[58:59], v[58:59], v[194:195] op_sel_hi:[1,0]
	v_pk_mul_f32 v[60:61], v[60:61], v[194:195] op_sel_hi:[1,0]
	v_pk_mul_f32 v[46:47], v[46:47], v[198:199] op_sel_hi:[1,0]
	v_pk_mul_f32 v[48:49], v[48:49], v[198:199] op_sel_hi:[1,0]
	v_pk_mul_f32 v[42:43], v[42:43], v[198:199] op_sel_hi:[1,0]
	v_pk_mul_f32 v[44:45], v[44:45], v[198:199] op_sel_hi:[1,0]
	v_pk_mul_f32 v[38:39], v[38:39], v[198:199] op_sel_hi:[1,0]
	v_pk_mul_f32 v[40:41], v[40:41], v[198:199] op_sel_hi:[1,0]
	v_pk_mul_f32 v[34:35], v[34:35], v[198:199] op_sel_hi:[1,0]
	v_pk_mul_f32 v[36:37], v[36:37], v[198:199] op_sel_hi:[1,0]
	v_pk_mul_f32 v[30:31], v[30:31], v[202:203] op_sel_hi:[1,0]
	v_pk_mul_f32 v[32:33], v[32:33], v[202:203] op_sel_hi:[1,0]
	v_pk_mul_f32 v[26:27], v[26:27], v[202:203] op_sel_hi:[1,0]
	v_pk_mul_f32 v[28:29], v[28:29], v[202:203] op_sel_hi:[1,0]
	v_pk_mul_f32 v[22:23], v[22:23], v[202:203] op_sel_hi:[1,0]
	v_pk_mul_f32 v[24:25], v[24:25], v[202:203] op_sel_hi:[1,0]
	v_pk_mul_f32 v[18:19], v[18:19], v[202:203] op_sel_hi:[1,0]
	v_pk_mul_f32 v[20:21], v[20:21], v[202:203] op_sel_hi:[1,0]
	v_pk_mul_f32 v[14:15], v[14:15], v[206:207] op_sel_hi:[1,0]
	v_pk_mul_f32 v[16:17], v[16:17], v[206:207] op_sel_hi:[1,0]
	v_pk_mul_f32 v[10:11], v[10:11], v[206:207] op_sel_hi:[1,0]
	v_pk_mul_f32 v[12:13], v[12:13], v[206:207] op_sel_hi:[1,0]
	v_pk_mul_f32 v[6:7], v[6:7], v[206:207] op_sel_hi:[1,0]
	v_pk_mul_f32 v[8:9], v[8:9], v[206:207] op_sel_hi:[1,0]
	v_pk_mul_f32 v[2:3], v[2:3], v[206:207] op_sel_hi:[1,0]
	v_pk_mul_f32 v[4:5], v[4:5], v[206:207] op_sel_hi:[1,0]
	v_cvt_pk_bf16_f32 v134, v134, v135
	v_cvt_pk_bf16_f32 v135, v136, v137
	v_cvt_pk_bf16_f32 v136, v130, v131
	v_cvt_pk_bf16_f32 v137, v132, v133
	v_add_u32_e32 v246, 0x0, v219
	global_store_dwordx4 v246, v[134:137], s[8:9]
	v_cvt_pk_bf16_f32 v118, v118, v119
	v_cvt_pk_bf16_f32 v119, v120, v121
	v_cvt_pk_bf16_f32 v120, v114, v115
	v_cvt_pk_bf16_f32 v121, v116, v117
	v_add_u32_e32 v247, 0xc000, v219
	global_store_dwordx4 v247, v[118:121], s[8:9]
	v_cvt_pk_bf16_f32 v102, v102, v103
	v_cvt_pk_bf16_f32 v103, v104, v105
	v_cvt_pk_bf16_f32 v104, v98, v99
	v_cvt_pk_bf16_f32 v105, v100, v101
	v_add_u32_e32 v246, 0x18000, v219
	global_store_dwordx4 v246, v[102:105], s[8:9]
	v_cvt_pk_bf16_f32 v86, v86, v87
	v_cvt_pk_bf16_f32 v87, v88, v89
	v_cvt_pk_bf16_f32 v88, v82, v83
	v_cvt_pk_bf16_f32 v89, v84, v85
	v_add_u32_e32 v247, 0x24000, v219
	global_store_dwordx4 v247, v[86:89], s[8:9]
	v_cvt_pk_bf16_f32 v70, v70, v71
	v_cvt_pk_bf16_f32 v71, v72, v73
	v_cvt_pk_bf16_f32 v72, v66, v67
	v_cvt_pk_bf16_f32 v73, v68, v69
	v_add_u32_e32 v246, 0x60000, v219
	global_store_dwordx4 v246, v[70:73], s[8:9]
	v_cvt_pk_bf16_f32 v46, v46, v47
	v_cvt_pk_bf16_f32 v47, v48, v49
	v_cvt_pk_bf16_f32 v48, v42, v43
	v_cvt_pk_bf16_f32 v49, v44, v45
	v_add_u32_e32 v247, 0x6c000, v219
	global_store_dwordx4 v247, v[46:49], s[8:9]
	v_cvt_pk_bf16_f32 v30, v30, v31
	v_cvt_pk_bf16_f32 v31, v32, v33
	v_cvt_pk_bf16_f32 v32, v26, v27
	v_cvt_pk_bf16_f32 v33, v28, v29
	v_add_u32_e32 v246, 0x78000, v219
	global_store_dwordx4 v246, v[30:33], s[8:9]
	v_cvt_pk_bf16_f32 v14, v14, v15
	v_cvt_pk_bf16_f32 v15, v16, v17
	v_cvt_pk_bf16_f32 v16, v10, v11
	v_cvt_pk_bf16_f32 v17, v12, v13
	v_add_u32_e32 v247, 0x84000, v219
	global_store_dwordx4 v247, v[14:17], s[8:9]
	s_waitcnt vmcnt(20)
	v_permlane32_swap_b32_e32 v126, v122
	v_permlane32_swap_b32_e32 v127, v123
	v_permlane32_swap_b32_e32 v128, v124
	v_permlane32_swap_b32_e32 v129, v125
	v_permlane32_swap_b32_e32 v110, v106
	v_permlane32_swap_b32_e32 v111, v107
	v_permlane32_swap_b32_e32 v112, v108
	v_permlane32_swap_b32_e32 v113, v109
	v_pk_mul_f32 v[130:131], v[126:127], v[228:229]
	v_pk_mul_f32 v[132:133], v[128:129], v[230:231]
	v_pk_mul_f32 v[114:115], v[110:111], v[236:237]
	v_pk_mul_f32 v[116:117], v[112:113], v[238:239]
	v_pk_fma_f32 v[130:131], v[122:123], v[232:233], v[130:131] neg_lo:[1,0,0] neg_hi:[1,0,0]
	v_pk_fma_f32 v[132:133], v[124:125], v[234:235], v[132:133] neg_lo:[1,0,0] neg_hi:[1,0,0]
	v_pk_fma_f32 v[114:115], v[106:107], v[50:51], v[114:115] neg_lo:[1,0,0] neg_hi:[1,0,0]
	v_pk_fma_f32 v[116:117], v[108:109], v[52:53], v[116:117] neg_lo:[1,0,0] neg_hi:[1,0,0]
	v_pk_mul_f32 v[122:123], v[122:123], v[228:229]
	v_pk_mul_f32 v[124:125], v[124:125], v[230:231]
	v_pk_mul_f32 v[106:107], v[106:107], v[236:237]
	v_pk_mul_f32 v[108:109], v[108:109], v[238:239]
	v_pk_fma_f32 v[122:123], v[126:127], v[232:233], v[122:123]
	v_pk_fma_f32 v[124:125], v[128:129], v[234:235], v[124:125]
	v_pk_fma_f32 v[106:107], v[110:111], v[50:51], v[106:107]
	v_pk_fma_f32 v[108:109], v[112:113], v[52:53], v[108:109]
	v_permlane32_swap_b32_e32 v130, v122
	v_permlane32_swap_b32_e32 v131, v123
	v_permlane32_swap_b32_e32 v132, v124
	v_permlane32_swap_b32_e32 v133, v125
	v_permlane32_swap_b32_e32 v114, v106
	v_permlane32_swap_b32_e32 v115, v107
	v_permlane32_swap_b32_e32 v116, v108
	v_permlane32_swap_b32_e32 v117, v109
	v_cvt_pk_bf16_f32 v126, v130, v131
	v_cvt_pk_bf16_f32 v127, v132, v133
	v_cvt_pk_bf16_f32 v128, v122, v123
	v_cvt_pk_bf16_f32 v129, v124, v125
	v_add_u32_e32 v246, 0x0, v219
	global_store_dwordx4 v246, v[126:129], s[8:9] offset:256
	v_cvt_pk_bf16_f32 v110, v114, v115
	v_cvt_pk_bf16_f32 v111, v116, v117
	v_cvt_pk_bf16_f32 v112, v106, v107
	v_cvt_pk_bf16_f32 v113, v108, v109
	v_add_u32_e32 v247, 0xc000, v219
	global_store_dwordx4 v247, v[110:113], s[8:9] offset:256
	s_waitcnt vmcnt(18)
	v_permlane32_swap_b32_e32 v94, v90
	v_permlane32_swap_b32_e32 v95, v91
	v_permlane32_swap_b32_e32 v96, v92
	v_permlane32_swap_b32_e32 v97, v93
	v_permlane32_swap_b32_e32 v78, v74
	v_permlane32_swap_b32_e32 v79, v75
	v_permlane32_swap_b32_e32 v80, v76
	v_permlane32_swap_b32_e32 v81, v77
	v_pk_mul_f32 v[98:99], v[94:95], v[54:55]
	v_pk_mul_f32 v[100:101], v[96:97], v[56:57]
	v_pk_mul_f32 v[82:83], v[78:79], v[188:189]
	v_pk_mul_f32 v[84:85], v[80:81], v[190:191]
	v_pk_fma_f32 v[98:99], v[90:91], v[184:185], v[98:99] neg_lo:[1,0,0] neg_hi:[1,0,0]
	v_pk_fma_f32 v[100:101], v[92:93], v[186:187], v[100:101] neg_lo:[1,0,0] neg_hi:[1,0,0]
	v_pk_fma_f32 v[82:83], v[74:75], v[214:215], v[82:83] neg_lo:[1,0,0] neg_hi:[1,0,0]
	v_pk_fma_f32 v[84:85], v[76:77], v[216:217], v[84:85] neg_lo:[1,0,0] neg_hi:[1,0,0]
	v_pk_mul_f32 v[90:91], v[90:91], v[54:55]
	v_pk_mul_f32 v[92:93], v[92:93], v[56:57]
	v_pk_mul_f32 v[74:75], v[74:75], v[188:189]
	v_pk_mul_f32 v[76:77], v[76:77], v[190:191]
	v_pk_fma_f32 v[90:91], v[94:95], v[184:185], v[90:91]
	v_pk_fma_f32 v[92:93], v[96:97], v[186:187], v[92:93]
	v_pk_fma_f32 v[74:75], v[78:79], v[214:215], v[74:75]
	v_pk_fma_f32 v[76:77], v[80:81], v[216:217], v[76:77]
	v_permlane32_swap_b32_e32 v98, v90
	v_permlane32_swap_b32_e32 v99, v91
	v_permlane32_swap_b32_e32 v100, v92
	v_permlane32_swap_b32_e32 v101, v93
	v_permlane32_swap_b32_e32 v82, v74
	v_permlane32_swap_b32_e32 v83, v75
	v_permlane32_swap_b32_e32 v84, v76
	v_permlane32_swap_b32_e32 v85, v77
	v_cvt_pk_bf16_f32 v94, v98, v99
	v_cvt_pk_bf16_f32 v95, v100, v101
	v_cvt_pk_bf16_f32 v96, v90, v91
	v_cvt_pk_bf16_f32 v97, v92, v93
	v_add_u32_e32 v246, 0x18000, v219
	global_store_dwordx4 v246, v[94:97], s[8:9] offset:256
	v_cvt_pk_bf16_f32 v78, v82, v83
	v_cvt_pk_bf16_f32 v79, v84, v85
	v_cvt_pk_bf16_f32 v80, v74, v75
	v_cvt_pk_bf16_f32 v81, v76, v77
	v_add_u32_e32 v247, 0x24000, v219
	global_store_dwordx4 v247, v[78:81], s[8:9] offset:256
	s_waitcnt vmcnt(16)
	v_permlane32_swap_b32_e32 v62, v58
	v_permlane32_swap_b32_e32 v63, v59
	v_permlane32_swap_b32_e32 v64, v60
	v_permlane32_swap_b32_e32 v65, v61
	v_permlane32_swap_b32_e32 v38, v34
	v_permlane32_swap_b32_e32 v39, v35
	v_permlane32_swap_b32_e32 v40, v36
	v_permlane32_swap_b32_e32 v41, v37
	v_pk_mul_f32 v[66:67], v[62:63], v[150:151]
	v_pk_mul_f32 v[68:69], v[64:65], v[152:153]
	v_pk_mul_f32 v[42:43], v[38:39], v[158:159]
	v_pk_mul_f32 v[44:45], v[40:41], v[160:161]
	v_pk_fma_f32 v[66:67], v[58:59], v[154:155], v[66:67] neg_lo:[1,0,0] neg_hi:[1,0,0]
	v_pk_fma_f32 v[68:69], v[60:61], v[156:157], v[68:69] neg_lo:[1,0,0] neg_hi:[1,0,0]
	v_pk_fma_f32 v[42:43], v[34:35], v[162:163], v[42:43] neg_lo:[1,0,0] neg_hi:[1,0,0]
	v_pk_fma_f32 v[44:45], v[36:37], v[164:165], v[44:45] neg_lo:[1,0,0] neg_hi:[1,0,0]
	v_pk_mul_f32 v[58:59], v[58:59], v[150:151]
	v_pk_mul_f32 v[60:61], v[60:61], v[152:153]
	v_pk_mul_f32 v[34:35], v[34:35], v[158:159]
	v_pk_mul_f32 v[36:37], v[36:37], v[160:161]
	v_pk_fma_f32 v[58:59], v[62:63], v[154:155], v[58:59]
	v_pk_fma_f32 v[60:61], v[64:65], v[156:157], v[60:61]
	v_pk_fma_f32 v[34:35], v[38:39], v[162:163], v[34:35]
	v_pk_fma_f32 v[36:37], v[40:41], v[164:165], v[36:37]
	v_permlane32_swap_b32_e32 v66, v58
	v_permlane32_swap_b32_e32 v67, v59
	v_permlane32_swap_b32_e32 v68, v60
	v_permlane32_swap_b32_e32 v69, v61
	v_permlane32_swap_b32_e32 v42, v34
	v_permlane32_swap_b32_e32 v43, v35
	v_permlane32_swap_b32_e32 v44, v36
	v_permlane32_swap_b32_e32 v45, v37
	v_cvt_pk_bf16_f32 v62, v66, v67
	v_cvt_pk_bf16_f32 v63, v68, v69
	v_cvt_pk_bf16_f32 v64, v58, v59
	v_cvt_pk_bf16_f32 v65, v60, v61
	v_add_u32_e32 v246, 0x60000, v219
	global_store_dwordx4 v246, v[62:65], s[8:9] offset:256
	v_cvt_pk_bf16_f32 v38, v42, v43
	v_cvt_pk_bf16_f32 v39, v44, v45
	v_cvt_pk_bf16_f32 v40, v34, v35
	v_cvt_pk_bf16_f32 v41, v36, v37
	v_add_u32_e32 v247, 0x6c000, v219
	global_store_dwordx4 v247, v[38:41], s[8:9] offset:256
	s_waitcnt vmcnt(14)
	v_permlane32_swap_b32_e32 v22, v18
	v_permlane32_swap_b32_e32 v23, v19
	v_permlane32_swap_b32_e32 v24, v20
	v_permlane32_swap_b32_e32 v25, v21
	v_permlane32_swap_b32_e32 v6, v2
	v_permlane32_swap_b32_e32 v7, v3
	v_permlane32_swap_b32_e32 v8, v4
	v_permlane32_swap_b32_e32 v9, v5
	v_pk_mul_f32 v[26:27], v[22:23], v[166:167]
	v_pk_mul_f32 v[28:29], v[24:25], v[168:169]
	v_pk_mul_f32 v[10:11], v[6:7], v[174:175]
	v_pk_mul_f32 v[12:13], v[8:9], v[176:177]
	v_pk_fma_f32 v[26:27], v[18:19], v[170:171], v[26:27] neg_lo:[1,0,0] neg_hi:[1,0,0]
	v_pk_fma_f32 v[28:29], v[20:21], v[172:173], v[28:29] neg_lo:[1,0,0] neg_hi:[1,0,0]
	v_pk_fma_f32 v[10:11], v[2:3], v[180:181], v[10:11] neg_lo:[1,0,0] neg_hi:[1,0,0]
	v_pk_fma_f32 v[12:13], v[4:5], v[182:183], v[12:13] neg_lo:[1,0,0] neg_hi:[1,0,0]
	v_pk_mul_f32 v[18:19], v[18:19], v[166:167]
	v_pk_mul_f32 v[20:21], v[20:21], v[168:169]
	v_pk_mul_f32 v[2:3], v[2:3], v[174:175]
	v_pk_mul_f32 v[4:5], v[4:5], v[176:177]
	v_pk_fma_f32 v[18:19], v[22:23], v[170:171], v[18:19]
	v_pk_fma_f32 v[20:21], v[24:25], v[172:173], v[20:21]
	v_pk_fma_f32 v[2:3], v[6:7], v[180:181], v[2:3]
	v_pk_fma_f32 v[4:5], v[8:9], v[182:183], v[4:5]
	v_permlane32_swap_b32_e32 v26, v18
	v_permlane32_swap_b32_e32 v27, v19
	v_permlane32_swap_b32_e32 v28, v20
	v_permlane32_swap_b32_e32 v29, v21
	v_permlane32_swap_b32_e32 v10, v2
	v_permlane32_swap_b32_e32 v11, v3
	v_permlane32_swap_b32_e32 v12, v4
	v_permlane32_swap_b32_e32 v13, v5
	v_cvt_pk_bf16_f32 v22, v26, v27
	v_cvt_pk_bf16_f32 v23, v28, v29
	v_cvt_pk_bf16_f32 v24, v18, v19
	v_cvt_pk_bf16_f32 v25, v20, v21
	v_add_u32_e32 v246, 0x78000, v219
	global_store_dwordx4 v246, v[22:25], s[8:9] offset:256
	v_cvt_pk_bf16_f32 v6, v10, v11
	v_cvt_pk_bf16_f32 v7, v12, v13
	v_cvt_pk_bf16_f32 v8, v2, v3
	v_cvt_pk_bf16_f32 v9, v4, v5
	v_add_u32_e32 v247, 0x84000, v219
	global_store_dwordx4 v247, v[6:9], s[8:9] offset:256
.Luq_end:
	v_mov_b64_e32 v[194:195], 0xc0
	v_mov_b64_e32 v[196:197], 0xbf
	v_mov_b64_e32 v[198:199], 0x180
	v_mov_b64_e32 v[200:201], 0x17f
	v_mov_b64_e32 v[202:203], 0x200
	v_mov_b64_e32 v[204:205], 0x1ff
	v_mov_b64_e32 v[206:207], 0x100
	v_mov_b64_e32 v[208:209], 0xff
	v_mov_b32_e32 v221, 0x3e38aa3b
	v_mov_b32_e32 v222, 0x7c
	v_mov_b32_e32 v223, 0x80
	v_mov_b32_e32 v224, 0x42800000
	s_and_b64 vcc, exec, s[36:37]
	s_mov_b64 s[2:3], -1
	s_cbranch_vccnz .LBB0_260
	s_andn2_b64 vcc, exec, s[6:7]
	s_cbranch_vccnz .LBB0_259
	s_barrier
	s_branch .LBB0_259
